# hyena filter-tap product: both channels of a workgroup computed in one pass over the hidden features (second channel's 4 tap rows ride in MFMA rows 4-7, stored via a 128 KiB scratch image in dead buff
# speedup vs baseline: 1.1829x; 1.0021x over previous
.LBB0_518:
	s_ashr_i32 s0, s5, 8
	v_readlane_b32 s1, v252, 47
	s_add_i32 s4, s1, s0
	v_readlane_b32 s0, v252, 40
	v_readlane_b32 s1, v252, 41
	v_mov_b32_e32 v146, v162
	s_and_b64 s[0:1], s[0:1], exec
	v_writelane_b32 v252, s5, 56
	s_cselect_b32 s68, s4, s5
	v_mov_b32_e32 v32, v146
	s_barrier
	v_readlane_b32 s4, v252, 22
	v_lshlrev_b32_e32 v2, 11, v32
	v_and_b32_e32 v144, 0x1000, v2
	v_readlane_b32 s6, v252, 24
	v_readlane_b32 s7, v252, 25
	v_bfe_u32 v33, v32, 5, 1
	s_ashr_i32 s69, s68, 31
	v_lshl_add_u64 v[0:1], s[6:7], 0, v[144:145]
	v_and_b32_e32 v144, 0x800, v2
	v_lshl_add_u64 v[0:1], v[0:1], 0, v[144:145]
	v_lshl_add_u64 v[0:1], s[68:69], 2, v[0:1]
	v_and_b32_e32 v144, 4, v32
	v_lshl_add_u64 v[0:1], v[0:1], 0, v[144:145]
	v_lshlrev_b32_e32 v144, 16, v33
	v_lshl_add_u64 v[0:1], v[0:1], 0, v[144:145]
	v_add_co_u32_e32 v2, vcc, s71, v0
	s_movk_i32 s0, 0x4000
	s_nop 0
	v_addc_co_u32_e32 v3, vcc, 0, v1, vcc
	v_add_co_u32_e32 v4, vcc, s0, v0
	s_movk_i32 s0, 0x6000
	s_nop 0
	v_addc_co_u32_e32 v5, vcc, 0, v1, vcc
	v_add_co_u32_e32 v6, vcc, s0, v0
	s_mov_b32 s0, 0x8000
	s_nop 0
	v_addc_co_u32_e32 v7, vcc, 0, v1, vcc
	v_add_co_u32_e32 v8, vcc, s0, v0
	s_mov_b32 s0, 0xa000
	s_nop 0
	v_addc_co_u32_e32 v9, vcc, 0, v1, vcc
	v_add_co_u32_e32 v10, vcc, s0, v0
	s_mov_b32 s0, 0xc000
	s_nop 0
	v_addc_co_u32_e32 v11, vcc, 0, v1, vcc
	v_add_co_u32_e32 v12, vcc, s0, v0
	s_mov_b32 s0, 0xe000
	s_nop 0
	v_addc_co_u32_e32 v13, vcc, 0, v1, vcc
	v_add_co_u32_e32 v14, vcc, s0, v0
	s_mov_b32 s0, 0x20000
	s_nop 0
	v_addc_co_u32_e32 v15, vcc, 0, v1, vcc
	global_load_dword v19, v[0:1], off
	global_load_dword v20, v[2:3], off
	global_load_dword v21, v[4:5], off
	global_load_dword v22, v[6:7], off
	global_load_dword v23, v[8:9], off
	global_load_dword v24, v[10:11], off
	global_load_dword v25, v[12:13], off
	global_load_dword v26, v[14:15], off
	v_add_co_u32_e32 v2, vcc, s0, v0
	s_mov_b32 s0, 0x22000
	s_nop 0
	v_addc_co_u32_e32 v3, vcc, 0, v1, vcc
	v_add_co_u32_e32 v4, vcc, s0, v0
	s_mov_b32 s0, 0x24000
	s_nop 0
	v_addc_co_u32_e32 v5, vcc, 0, v1, vcc
	v_add_co_u32_e32 v6, vcc, s0, v0
	s_mov_b32 s0, 0x26000
	s_nop 0
	v_addc_co_u32_e32 v7, vcc, 0, v1, vcc
	v_add_co_u32_e32 v8, vcc, s0, v0
	s_mov_b32 s0, 0x28000
	s_nop 0
	v_addc_co_u32_e32 v9, vcc, 0, v1, vcc
	v_add_co_u32_e32 v10, vcc, s0, v0
	s_mov_b32 s0, 0x2a000
	s_nop 0
	v_addc_co_u32_e32 v11, vcc, 0, v1, vcc
	v_add_co_u32_e32 v12, vcc, s0, v0
	s_mov_b32 s0, 0x2c000
	s_nop 0
	v_addc_co_u32_e32 v13, vcc, 0, v1, vcc
	v_add_co_u32_e32 v14, vcc, s0, v0
	s_mov_b32 s0, 0x2e000
	s_nop 0
	v_addc_co_u32_e32 v15, vcc, 0, v1, vcc
	v_add_co_u32_e32 v16, vcc, s0, v0
	s_mov_b32 s0, 0x40000
	s_nop 0
	v_addc_co_u32_e32 v17, vcc, 0, v1, vcc
	global_load_dword v27, v[2:3], off
	global_load_dword v28, v[4:5], off
	global_load_dword v29, v[6:7], off
	global_load_dword v30, v[8:9], off
	global_load_dword v31, v[10:11], off
	global_load_dword v34, v[12:13], off
	global_load_dword v35, v[14:15], off
	global_load_dword v36, v[16:17], off
	v_add_co_u32_e32 v2, vcc, s0, v0
	s_mov_b32 s0, 0x42000
	s_nop 0
	v_addc_co_u32_e32 v3, vcc, 0, v1, vcc
	v_add_co_u32_e32 v4, vcc, s0, v0
	s_mov_b32 s0, 0x44000
	s_nop 0
	v_addc_co_u32_e32 v5, vcc, 0, v1, vcc
	v_add_co_u32_e32 v6, vcc, s0, v0
	s_mov_b32 s0, 0x46000
	s_nop 0
	v_addc_co_u32_e32 v7, vcc, 0, v1, vcc
	v_add_co_u32_e32 v8, vcc, s0, v0
	s_mov_b32 s0, 0x48000
	s_nop 0
	v_addc_co_u32_e32 v9, vcc, 0, v1, vcc
	v_add_co_u32_e32 v10, vcc, s0, v0
	s_mov_b32 s0, 0x4a000
	s_nop 0
	v_addc_co_u32_e32 v11, vcc, 0, v1, vcc
	v_add_co_u32_e32 v12, vcc, s0, v0
	s_mov_b32 s0, 0x4c000
	s_nop 0
	v_addc_co_u32_e32 v13, vcc, 0, v1, vcc
	v_add_co_u32_e32 v14, vcc, s0, v0
	s_mov_b32 s0, 0x4e000
	s_nop 0
	v_addc_co_u32_e32 v15, vcc, 0, v1, vcc
	v_add_co_u32_e32 v16, vcc, s0, v0
	s_mov_b32 s0, 0x60000
	s_nop 0
	v_addc_co_u32_e32 v17, vcc, 0, v1, vcc
	global_load_dword v37, v[2:3], off
	global_load_dword v38, v[4:5], off
	global_load_dword v39, v[6:7], off
	global_load_dword v40, v[8:9], off
	global_load_dword v41, v[10:11], off
	global_load_dword v42, v[12:13], off
	global_load_dword v43, v[14:15], off
	global_load_dword v44, v[16:17], off
	v_add_co_u32_e32 v2, vcc, s0, v0
	s_mov_b32 s0, 0x62000
	s_nop 0
	v_addc_co_u32_e32 v3, vcc, 0, v1, vcc
	v_add_co_u32_e32 v4, vcc, s0, v0
	s_mov_b32 s0, 0x64000
	s_nop 0
	v_addc_co_u32_e32 v5, vcc, 0, v1, vcc
	v_add_co_u32_e32 v6, vcc, s0, v0
	s_mov_b32 s0, 0x66000
	s_nop 0
	v_addc_co_u32_e32 v7, vcc, 0, v1, vcc
	v_add_co_u32_e32 v8, vcc, s0, v0
	s_mov_b32 s0, 0x68000
	s_nop 0
	v_addc_co_u32_e32 v9, vcc, 0, v1, vcc
	v_add_co_u32_e32 v10, vcc, s0, v0
	s_mov_b32 s0, 0x6a000
	s_nop 0
	v_addc_co_u32_e32 v11, vcc, 0, v1, vcc
	v_add_co_u32_e32 v12, vcc, s0, v0
	s_mov_b32 s0, 0x6c000
	s_nop 0
	v_addc_co_u32_e32 v13, vcc, 0, v1, vcc
	v_add_co_u32_e32 v14, vcc, s0, v0
	s_mov_b32 s0, 0x6e000
	s_nop 0
	v_addc_co_u32_e32 v15, vcc, 0, v1, vcc
	v_add_co_u32_e32 v0, vcc, s0, v0
	v_add_u32_e32 v18, s68, v33
	v_cvt_f32_i32_e32 v18, v18
	s_nop 0
	v_addc_co_u32_e32 v1, vcc, 0, v1, vcc
	global_load_dword v2, v[2:3], off
	s_nop 0
	global_load_dword v3, v[4:5], off
	s_nop 0
	global_load_dword v4, v[6:7], off
	global_load_dword v5, v[8:9], off
	s_nop 0
	global_load_dword v6, v[10:11], off
	global_load_dword v7, v[12:13], off
	global_load_dword v8, v[14:15], off
	s_nop 0
	global_load_dword v0, v[0:1], off
	s_mov_b32 s4, 0x43ff8000
	v_div_scale_f32 v1, s[0:1], s4, s4, v18
	v_rcp_f32_e32 v9, v1
	v_add_u32_e32 v13, s68, v33
	v_sub_u32_e32 v13, 0x1ff, v13
	v_cvt_f32_i32_e32 v13, v13
	v_readlane_b32 s5, v252, 23
	v_fma_f32 v10, -v1, v9, 1.0
	v_fmac_f32_e32 v9, v10, v9
	v_div_scale_f32 v10, vcc, v18, s4, v18
	v_mul_f32_e32 v11, v10, v9
	v_fma_f32 v12, -v1, v11, v10
	v_fmac_f32_e32 v11, v12, v9
	v_fma_f32 v1, -v1, v11, v10
	v_div_scale_f32 v10, s[0:1], s4, s4, v13
	v_rcp_f32_e32 v12, v10
	v_div_fmas_f32 v1, v1, v9, v11
	v_div_fixup_f32 v1, v1, s4, v18
	v_fmamk_f32 v144, v1, 0xc1447cbd, v152
	v_fma_f32 v1, -v10, v12, 1.0
	v_fmac_f32_e32 v12, v1, v12
	v_div_scale_f32 v1, vcc, v13, s4, v13
	v_mul_f32_e32 v9, v1, v12
	v_fma_f32 v11, -v10, v9, v1
	v_fmac_f32_e32 v9, v11, v12
	v_fma_f32 v1, -v10, v9, v1
	v_div_fmas_f32 v1, v1, v12, v9
	v_and_b32_e32 v9, 31, v32
	v_div_fixup_f32 v1, v1, s4, v13
	v_cmp_gt_u32_e32 vcc, 8, v9
	v_fmamk_f32 v147, v1, 0xc1447cbd, v152
	v_cmp_eq_u32_e64 s[0:1], 0, v33
	s_waitcnt vmcnt(31)
	v_cndmask_b32_e32 v1, 0, v19, vcc
	s_waitcnt vmcnt(30)
	v_cndmask_b32_e32 v10, 0, v20, vcc
	v_cvt_pk_bf16_f32 v16, v1, v10
	s_waitcnt vmcnt(23)
	v_cndmask_b32_e32 v1, 0, v27, vcc
	s_waitcnt vmcnt(22)
	v_cndmask_b32_e32 v10, 0, v28, vcc
	v_cvt_pk_bf16_f32 v20, v1, v10
	s_waitcnt vmcnt(15)
	v_cndmask_b32_e32 v1, 0, v37, vcc
	s_waitcnt vmcnt(14)
	v_cndmask_b32_e32 v10, 0, v38, vcc
	v_cndmask_b32_e32 v13, 0, v23, vcc
	v_cndmask_b32_e32 v14, 0, v24, vcc
	v_cvt_pk_bf16_f32 v24, v1, v10
	v_cvt_pk_bf16_f32 v18, v13, v14
	v_cndmask_b32_e32 v13, 0, v31, vcc
	v_cndmask_b32_e32 v11, 0, v21, vcc
	v_cndmask_b32_e32 v12, 0, v22, vcc
	v_cndmask_b32_e32 v15, 0, v25, vcc
	v_cndmask_b32_e32 v19, 0, v26, vcc
	v_cvt_pk_bf16_f32 v17, v11, v12
	v_cvt_pk_bf16_f32 v19, v15, v19
	v_cndmask_b32_e32 v11, 0, v29, vcc
	v_cndmask_b32_e32 v12, 0, v30, vcc
	v_cndmask_b32_e32 v14, 0, v34, vcc
	v_cndmask_b32_e32 v15, 0, v35, vcc
	v_cndmask_b32_e32 v23, 0, v36, vcc
	v_cvt_pk_bf16_f32 v21, v11, v12
	v_cvt_pk_bf16_f32 v22, v13, v14
	v_cvt_pk_bf16_f32 v23, v15, v23
	s_waitcnt vmcnt(13)
	v_cndmask_b32_e32 v11, 0, v39, vcc
	s_waitcnt vmcnt(12)
	v_cndmask_b32_e32 v12, 0, v40, vcc
	s_waitcnt vmcnt(11)
	v_cndmask_b32_e32 v13, 0, v41, vcc
	s_waitcnt vmcnt(10)
	v_cndmask_b32_e32 v14, 0, v42, vcc
	s_waitcnt vmcnt(9)
	v_cndmask_b32_e32 v15, 0, v43, vcc
	s_waitcnt vmcnt(8)
	v_cndmask_b32_e32 v27, 0, v44, vcc
	v_cvt_pk_bf16_f32 v25, v11, v12
	v_cvt_pk_bf16_f32 v26, v13, v14
	v_cvt_pk_bf16_f32 v27, v15, v27
	s_mov_b64 s[4:5], 0
	s_waitcnt vmcnt(7)
	v_cndmask_b32_e32 v1, 0, v2, vcc
	s_waitcnt vmcnt(6)
	v_cndmask_b32_e32 v2, 0, v3, vcc
	s_waitcnt vmcnt(5)
	v_cndmask_b32_e32 v3, 0, v4, vcc
	s_waitcnt vmcnt(4)
	v_cndmask_b32_e32 v4, 0, v5, vcc
	s_waitcnt vmcnt(3)
	v_cndmask_b32_e32 v5, 0, v6, vcc
	s_waitcnt vmcnt(2)
	v_cndmask_b32_e32 v6, 0, v7, vcc
	s_waitcnt vmcnt(1)
	v_cndmask_b32_e32 v7, 0, v8, vcc
	s_waitcnt vmcnt(0)
	v_cndmask_b32_e32 v0, 0, v0, vcc
	v_cvt_pk_bf16_f32 v31, v7, v0
	v_lshlrev_b32_e32 v0, 4, v32
	v_and_b32_e32 v0, 0xfffffc00, v0
	v_cvt_pk_bf16_f32 v28, v1, v2
	v_ashrrev_i32_e32 v149, 31, v0
	v_or_b32_e32 v148, v0, v9
	v_lshlrev_b32_e32 v2, 6, v32
	v_lshlrev_b64 v[0:1], 7, v[148:149]
	v_and_b32_e32 v2, 0xfffff000, v2
	v_lshl_or_b32 v149, v9, 2, v2
	v_lshl_or_b32 v0, v33, 4, v0
	v_cvt_pk_bf16_f32 v29, v3, v4
	v_cvt_pk_bf16_f32 v30, v5, v6
	v_sub_u32_e32 v155, 0, v149
	v_sub_u32_e32 v0, v148, v9
	v_lshlrev_b32_e32 v0, 7, v0
	v_lshl_add_u32 v0, v9, 4, v0
	v_lshl_add_u32 v0, v33, 9, v0
	v_mov_b32_e32 v1, 0
	v_lshl_add_u64 v[150:151], s[86:87], 0, v[0:1]
	v_readlane_b32 s8, v252, 26
	v_readlane_b32 s9, v252, 27
	v_readlane_b32 s10, v252, 28
	v_readlane_b32 s11, v252, 29
	v_readlane_b32 s12, v252, 30
	v_readlane_b32 s13, v252, 31
	v_readlane_b32 s14, v252, 32
	v_readlane_b32 s15, v252, 33
	v_readlane_b32 s16, v252, 34
	v_readlane_b32 s17, v252, 35
	v_readlane_b32 s18, v252, 36
	v_readlane_b32 s19, v252, 37
	s_branch .LBB0_520
.LBB0_520:
	v_readlane_b32 s100, v252, 56
	s_and_b32 s6, s100, 0xff
	s_lshl_b32 s101, s6, 17
	s_cmpk_ge_u32 s6, 0x80
	s_cselect_b32 s7, 0xb000000, 0
	s_add_u32 s101, s101, s7
	s_cmpk_ge_u32 s6, 0xd0
	s_cselect_b32 s7, 0x1000000, 0
	s_add_u32 s101, s101, s7
	s_cmpk_ge_u32 s100, 0x100
	s_cbranch_scc1 .Ltp3_copy_L0
	v_mov_b32_e32 v188, s101
	v_subrev_u32_e32 v180, s86, v150
	v_add_u32_e32 v181, 0x1000, v180
	v_add_u32_e32 v182, 0x2000, v180
	v_add_u32_e32 v183, 0x3000, v180
	v_add_u32_e32 v184, 0x4000, v180
	v_add_u32_e32 v185, 0x5000, v180
	v_add_u32_e32 v186, 0x6000, v180
	v_add_u32_e32 v187, 0x7000, v180
	s_add_u32 s98, s86, 0xe200000
	s_addc_u32 s99, s87, 0
	global_load_dwordx4 v[164:167], v180, s[98:99]
	global_load_dwordx4 v[168:171], v180, s[98:99] offset:1024
	global_load_dwordx4 v[172:175], v180, s[98:99] offset:2048
	global_load_dwordx4 v[176:179], v180, s[98:99] offset:3072
	global_load_dwordx4 v[140:143], v181, s[98:99]
	global_load_dwordx4 v[136:139], v181, s[98:99] offset:1024
	global_load_dwordx4 v[132:135], v181, s[98:99] offset:2048
	global_load_dwordx4 v[128:131], v181, s[98:99] offset:3072
	global_load_dwordx4 v[124:127], v182, s[98:99]
	global_load_dwordx4 v[120:123], v182, s[98:99] offset:1024
	global_load_dwordx4 v[116:119], v182, s[98:99] offset:2048
	global_load_dwordx4 v[112:115], v182, s[98:99] offset:3072
	global_load_dwordx4 v[108:111], v183, s[98:99]
	global_load_dwordx4 v[104:107], v183, s[98:99] offset:1024
	global_load_dwordx4 v[100:103], v183, s[98:99] offset:2048
	global_load_dwordx4 v[96:99], v183, s[98:99] offset:3072
	global_load_dwordx4 v[92:95], v184, s[98:99]
	global_load_dwordx4 v[88:91], v184, s[98:99] offset:1024
	global_load_dwordx4 v[84:87], v184, s[98:99] offset:2048
	global_load_dwordx4 v[80:83], v184, s[98:99] offset:3072
	global_load_dwordx4 v[76:79], v185, s[98:99]
	global_load_dwordx4 v[68:71], v185, s[98:99] offset:1024
	global_load_dwordx4 v[56:59], v185, s[98:99] offset:2048
	global_load_dwordx4 v[48:51], v185, s[98:99] offset:3072
	global_load_dwordx4 v[72:75], v186, s[98:99]
	global_load_dwordx4 v[60:63], v186, s[98:99] offset:1024
	global_load_dwordx4 v[64:67], v186, s[98:99] offset:2048
	global_load_dwordx4 v[52:55], v186, s[98:99] offset:3072
	global_load_dwordx4 v[36:39], v187, s[98:99]
	global_load_dwordx4 v[32:35], v187, s[98:99] offset:1024
	global_load_dwordx4 v[40:43], v187, s[98:99] offset:2048
	global_load_dwordx4 v[44:47], v187, s[98:99] offset:3072
	s_add_u32 s98, s98, 0x8000
	s_addc_u32 s99, s99, 0
	v_add_u32_e32 v157, 16, v149
	v_add_u32_e32 v156, 16, v155
	v_add_u32_e32 v189, v188, v149
	v_add_u32_e32 v190, v188, v155
	v_add_u32_e32 v191, 0xf000, v190
	s_waitcnt vmcnt(31)
	v_mfma_f32_32x32x16_bf16 v[0:15], v[16:19], v[164:167], 0
	s_waitcnt vmcnt(30)
	v_mfma_f32_32x32x16_bf16 v[0:15], v[20:23], v[168:171], v[0:15]
	s_waitcnt vmcnt(29)
	v_mfma_f32_32x32x16_bf16 v[0:15], v[24:27], v[172:175], v[0:15]
	s_waitcnt vmcnt(28)
	v_mfma_f32_32x32x16_bf16 v[0:15], v[28:31], v[176:179], v[0:15]
	global_load_dwordx4 v[164:167], v180, s[98:99]
	global_load_dwordx4 v[168:171], v180, s[98:99] offset:1024
	global_load_dwordx4 v[172:175], v180, s[98:99] offset:2048
	global_load_dwordx4 v[176:179], v180, s[98:99] offset:3072
	s_and_saveexec_b64 s[6:7], s[0:1]
	s_cbranch_execz .Ltp3_L0_f_a0
	s_nop 7
	v_cvt_f32_i32_e32 v4, v148
	v_mul_f32_e32 v4, 0xb9000400, v4
	v_mul_f32_e64 v5, |v144|, v4
	v_mul_f32_e64 v4, |v147|, v4
	v_mul_f32_e32 v5, 0x3fb8aa3b, v5
	v_mul_f32_e32 v4, 0x3fb8aa3b, v4
	v_exp_f32_e32 v5, v5
	v_exp_f32_e32 v4, v4
	v_mul_f32_e32 v0, v5, v0
	v_mul_f32_e32 v1, v4, v1
	v_mul_f32_e32 v2, v5, v2
	ds_write_b32 v157, v0
	ds_write_b32 v156, v1 offset:65532
	v_add_u32_e32 v0, 0x10000, v157
	ds_write_b32 v0, v2
	v_mul_f32_e32 v0, v4, v3
	v_add_u32_e32 v1, 0x1fffc, v156
	ds_write_b32 v1, v0
.Ltp3_L0_f_a0:
	s_or_b64 exec, exec, s[6:7]
	s_mov_b64 s[6:7], exec
	s_andn2_b64 exec, exec, s[0:1]
	s_cbranch_execz .Ltp3_L0_f_b0
	s_nop 7
	v_cvt_f32_i32_e32 v4, v148
	v_mul_f32_e32 v4, 0xb9000400, v4
	v_mul_f32_e64 v5, |v144|, v4
	v_mul_f32_e64 v4, |v147|, v4
	v_mul_f32_e32 v5, 0x3fb8aa3b, v5
	v_mul_f32_e32 v4, 0x3fb8aa3b, v4
	v_exp_f32_e32 v5, v5
	v_exp_f32_e32 v4, v4
	v_mul_f32_e32 v0, v5, v0
	v_mul_f32_e32 v1, v4, v1
	v_mul_f32_e32 v2, v5, v2
	global_store_dword v189, v0, s[86:87]
	global_store_dword v191, v1, s[86:87] offset:4092
	v_add_u32_e32 v0, 0x10000, v189
	global_store_dword v0, v2, s[86:87]
	v_mul_f32_e32 v0, v4, v3
	v_add_u32_e32 v1, 0x1fffc, v190
	global_store_dword v1, v0, s[86:87]
.Ltp3_L0_f_b0:
	s_mov_b64 exec, s[6:7]
	s_waitcnt vmcnt(35)
	v_mfma_f32_32x32x16_bf16 v[0:15], v[16:19], v[140:143], 0
	s_waitcnt vmcnt(34)
	v_mfma_f32_32x32x16_bf16 v[0:15], v[20:23], v[136:139], v[0:15]
	s_waitcnt vmcnt(33)
	v_mfma_f32_32x32x16_bf16 v[0:15], v[24:27], v[132:135], v[0:15]
	s_waitcnt vmcnt(32)
	v_mfma_f32_32x32x16_bf16 v[0:15], v[28:31], v[128:131], v[0:15]
	global_load_dwordx4 v[140:143], v181, s[98:99]
	global_load_dwordx4 v[136:139], v181, s[98:99] offset:1024
	global_load_dwordx4 v[132:135], v181, s[98:99] offset:2048
	global_load_dwordx4 v[128:131], v181, s[98:99] offset:3072
	s_and_saveexec_b64 s[6:7], s[0:1]
	s_cbranch_execz .Ltp3_L0_f_a1
	s_nop 9
	v_add_u32_e32 v4, 32, v148
	v_cvt_f32_i32_e32 v4, v4
	v_mul_f32_e32 v4, 0xb9000400, v4
	v_mul_f32_e64 v5, |v144|, v4
	v_mul_f32_e64 v4, |v147|, v4
	v_mul_f32_e32 v5, 0x3fb8aa3b, v5
	v_mul_f32_e32 v4, 0x3fb8aa3b, v4
	v_exp_f32_e32 v5, v5
	v_exp_f32_e32 v4, v4
	v_mul_f32_e32 v0, v5, v0
	v_mul_f32_e32 v1, v4, v1
	v_mul_f32_e32 v2, v5, v2
	ds_write_b32 v157, v0 offset:128
	ds_write_b32 v156, v1 offset:65404
	v_add_u32_e32 v0, 0x10080, v157
	ds_write_b32 v0, v2
	v_mul_f32_e32 v0, v4, v3
	v_add_u32_e32 v1, 0x1ff7c, v156
	ds_write_b32 v1, v0
.Ltp3_L0_f_a1:
	s_or_b64 exec, exec, s[6:7]
	s_mov_b64 s[6:7], exec
	s_andn2_b64 exec, exec, s[0:1]
	s_cbranch_execz .Ltp3_L0_f_b1
	s_nop 9
	v_add_u32_e32 v4, 32, v148
	v_cvt_f32_i32_e32 v4, v4
	v_mul_f32_e32 v4, 0xb9000400, v4
	v_mul_f32_e64 v5, |v144|, v4
	v_mul_f32_e64 v4, |v147|, v4
	v_mul_f32_e32 v5, 0x3fb8aa3b, v5
	v_mul_f32_e32 v4, 0x3fb8aa3b, v4
	v_exp_f32_e32 v5, v5
	v_exp_f32_e32 v4, v4
	v_mul_f32_e32 v0, v5, v0
	v_mul_f32_e32 v1, v4, v1
	v_mul_f32_e32 v2, v5, v2
	global_store_dword v189, v0, s[86:87] offset:128
	global_store_dword v191, v1, s[86:87] offset:3964
	v_add_u32_e32 v0, 0x10080, v189
	global_store_dword v0, v2, s[86:87]
	v_mul_f32_e32 v0, v4, v3
	v_add_u32_e32 v1, 0x1ff7c, v190
	global_store_dword v1, v0, s[86:87]
.Ltp3_L0_f_b1:
	s_mov_b64 exec, s[6:7]
	s_waitcnt vmcnt(39)
	v_mfma_f32_32x32x16_bf16 v[0:15], v[16:19], v[124:127], 0
	s_waitcnt vmcnt(38)
	v_mfma_f32_32x32x16_bf16 v[0:15], v[20:23], v[120:123], v[0:15]
	s_waitcnt vmcnt(37)
	v_mfma_f32_32x32x16_bf16 v[0:15], v[24:27], v[116:119], v[0:15]
	s_waitcnt vmcnt(36)
	v_mfma_f32_32x32x16_bf16 v[0:15], v[28:31], v[112:115], v[0:15]
	global_load_dwordx4 v[124:127], v182, s[98:99]
	global_load_dwordx4 v[120:123], v182, s[98:99] offset:1024
	global_load_dwordx4 v[116:119], v182, s[98:99] offset:2048
	global_load_dwordx4 v[112:115], v182, s[98:99] offset:3072
	s_and_saveexec_b64 s[6:7], s[0:1]
	s_cbranch_execz .Ltp3_L0_f_a2
	s_nop 9
	v_add_u32_e32 v4, 64, v148
	v_cvt_f32_i32_e32 v4, v4
	v_mul_f32_e32 v4, 0xb9000400, v4
	v_mul_f32_e64 v5, |v144|, v4
	v_mul_f32_e64 v4, |v147|, v4
	v_mul_f32_e32 v5, 0x3fb8aa3b, v5
	v_mul_f32_e32 v4, 0x3fb8aa3b, v4
	v_exp_f32_e32 v5, v5
	v_exp_f32_e32 v4, v4
	v_mul_f32_e32 v0, v5, v0
	v_mul_f32_e32 v1, v4, v1
	v_mul_f32_e32 v2, v5, v2
	ds_write_b32 v157, v0 offset:256
	ds_write_b32 v156, v1 offset:65276
	v_add_u32_e32 v0, 0x10100, v157
	ds_write_b32 v0, v2
	v_mul_f32_e32 v0, v4, v3
	v_add_u32_e32 v1, 0x1fefc, v156
	ds_write_b32 v1, v0
.Ltp3_L0_f_a2:
	s_or_b64 exec, exec, s[6:7]
	s_mov_b64 s[6:7], exec
	s_andn2_b64 exec, exec, s[0:1]
	s_cbranch_execz .Ltp3_L0_f_b2
	s_nop 9
	v_add_u32_e32 v4, 64, v148
	v_cvt_f32_i32_e32 v4, v4
	v_mul_f32_e32 v4, 0xb9000400, v4
	v_mul_f32_e64 v5, |v144|, v4
	v_mul_f32_e64 v4, |v147|, v4
	v_mul_f32_e32 v5, 0x3fb8aa3b, v5
	v_mul_f32_e32 v4, 0x3fb8aa3b, v4
	v_exp_f32_e32 v5, v5
	v_exp_f32_e32 v4, v4
	v_mul_f32_e32 v0, v5, v0
	v_mul_f32_e32 v1, v4, v1
	v_mul_f32_e32 v2, v5, v2
	global_store_dword v189, v0, s[86:87] offset:256
	global_store_dword v191, v1, s[86:87] offset:3836
	v_add_u32_e32 v0, 0x10100, v189
	global_store_dword v0, v2, s[86:87]
	v_mul_f32_e32 v0, v4, v3
	v_add_u32_e32 v1, 0x1fefc, v190
	global_store_dword v1, v0, s[86:87]
.Ltp3_L0_f_b2:
	s_mov_b64 exec, s[6:7]
	s_waitcnt vmcnt(43)
	v_mfma_f32_32x32x16_bf16 v[0:15], v[16:19], v[108:111], 0
	s_waitcnt vmcnt(42)
	v_mfma_f32_32x32x16_bf16 v[0:15], v[20:23], v[104:107], v[0:15]
	s_waitcnt vmcnt(41)
	v_mfma_f32_32x32x16_bf16 v[0:15], v[24:27], v[100:103], v[0:15]
	s_waitcnt vmcnt(40)
	v_mfma_f32_32x32x16_bf16 v[0:15], v[28:31], v[96:99], v[0:15]
	global_load_dwordx4 v[108:111], v183, s[98:99]
	global_load_dwordx4 v[104:107], v183, s[98:99] offset:1024
	global_load_dwordx4 v[100:103], v183, s[98:99] offset:2048
	global_load_dwordx4 v[96:99], v183, s[98:99] offset:3072
	s_and_saveexec_b64 s[6:7], s[0:1]
	s_cbranch_execz .Ltp3_L0_f_a3
	s_nop 9
	v_add_u32_e32 v4, 0x60, v148
	v_cvt_f32_i32_e32 v4, v4
	v_mul_f32_e32 v4, 0xb9000400, v4
	v_mul_f32_e64 v5, |v144|, v4
	v_mul_f32_e64 v4, |v147|, v4
	v_mul_f32_e32 v5, 0x3fb8aa3b, v5
	v_mul_f32_e32 v4, 0x3fb8aa3b, v4
	v_exp_f32_e32 v5, v5
	v_exp_f32_e32 v4, v4
	v_mul_f32_e32 v0, v5, v0
	v_mul_f32_e32 v1, v4, v1
	v_mul_f32_e32 v2, v5, v2
	ds_write_b32 v157, v0 offset:384
	ds_write_b32 v156, v1 offset:65148
	v_add_u32_e32 v0, 0x10180, v157
	ds_write_b32 v0, v2
	v_mul_f32_e32 v0, v4, v3
	v_add_u32_e32 v1, 0x1fe7c, v156
	ds_write_b32 v1, v0
.Ltp3_L0_f_a3:
	s_or_b64 exec, exec, s[6:7]
	s_mov_b64 s[6:7], exec
	s_andn2_b64 exec, exec, s[0:1]
	s_cbranch_execz .Ltp3_L0_f_b3
	s_nop 9
	v_add_u32_e32 v4, 0x60, v148
	v_cvt_f32_i32_e32 v4, v4
	v_mul_f32_e32 v4, 0xb9000400, v4
	v_mul_f32_e64 v5, |v144|, v4
	v_mul_f32_e64 v4, |v147|, v4
	v_mul_f32_e32 v5, 0x3fb8aa3b, v5
	v_mul_f32_e32 v4, 0x3fb8aa3b, v4
	v_exp_f32_e32 v5, v5
	v_exp_f32_e32 v4, v4
	v_mul_f32_e32 v0, v5, v0
	v_mul_f32_e32 v1, v4, v1
	v_mul_f32_e32 v2, v5, v2
	global_store_dword v189, v0, s[86:87] offset:384
	global_store_dword v191, v1, s[86:87] offset:3708
	v_add_u32_e32 v0, 0x10180, v189
	global_store_dword v0, v2, s[86:87]
	v_mul_f32_e32 v0, v4, v3
	v_add_u32_e32 v1, 0x1fe7c, v190
	global_store_dword v1, v0, s[86:87]
.Ltp3_L0_f_b3:
	s_mov_b64 exec, s[6:7]
	s_waitcnt vmcnt(47)
	v_mfma_f32_32x32x16_bf16 v[0:15], v[16:19], v[92:95], 0
	s_waitcnt vmcnt(46)
	v_mfma_f32_32x32x16_bf16 v[0:15], v[20:23], v[88:91], v[0:15]
	s_waitcnt vmcnt(45)
	v_mfma_f32_32x32x16_bf16 v[0:15], v[24:27], v[84:87], v[0:15]
	s_waitcnt vmcnt(44)
	v_mfma_f32_32x32x16_bf16 v[0:15], v[28:31], v[80:83], v[0:15]
	global_load_dwordx4 v[92:95], v184, s[98:99]
	global_load_dwordx4 v[88:91], v184, s[98:99] offset:1024
	global_load_dwordx4 v[84:87], v184, s[98:99] offset:2048
	global_load_dwordx4 v[80:83], v184, s[98:99] offset:3072
	s_and_saveexec_b64 s[6:7], s[0:1]
	s_cbranch_execz .Ltp3_L0_f_a4
	s_nop 9
	v_add_u32_e32 v4, 0x80, v148
	v_cvt_f32_i32_e32 v4, v4
	v_mul_f32_e32 v4, 0xb9000400, v4
	v_mul_f32_e64 v5, |v144|, v4
	v_mul_f32_e64 v4, |v147|, v4
	v_mul_f32_e32 v5, 0x3fb8aa3b, v5
	v_mul_f32_e32 v4, 0x3fb8aa3b, v4
	v_exp_f32_e32 v5, v5
	v_exp_f32_e32 v4, v4
	v_mul_f32_e32 v0, v5, v0
	v_mul_f32_e32 v1, v4, v1
	v_mul_f32_e32 v2, v5, v2
	ds_write_b32 v157, v0 offset:512
	ds_write_b32 v156, v1 offset:65020
	v_add_u32_e32 v0, 0x10200, v157
	ds_write_b32 v0, v2
	v_mul_f32_e32 v0, v4, v3
	v_add_u32_e32 v1, 0x1fdfc, v156
	ds_write_b32 v1, v0
.Ltp3_L0_f_a4:
	s_or_b64 exec, exec, s[6:7]
	s_mov_b64 s[6:7], exec
	s_andn2_b64 exec, exec, s[0:1]
	s_cbranch_execz .Ltp3_L0_f_b4
	s_nop 9
	v_add_u32_e32 v4, 0x80, v148
	v_cvt_f32_i32_e32 v4, v4
	v_mul_f32_e32 v4, 0xb9000400, v4
	v_mul_f32_e64 v5, |v144|, v4
	v_mul_f32_e64 v4, |v147|, v4
	v_mul_f32_e32 v5, 0x3fb8aa3b, v5
	v_mul_f32_e32 v4, 0x3fb8aa3b, v4
	v_exp_f32_e32 v5, v5
	v_exp_f32_e32 v4, v4
	v_mul_f32_e32 v0, v5, v0
	v_mul_f32_e32 v1, v4, v1
	v_mul_f32_e32 v2, v5, v2
	global_store_dword v189, v0, s[86:87] offset:512
	global_store_dword v191, v1, s[86:87] offset:3580
	v_add_u32_e32 v0, 0x10200, v189
	global_store_dword v0, v2, s[86:87]
	v_mul_f32_e32 v0, v4, v3
	v_add_u32_e32 v1, 0x1fdfc, v190
	global_store_dword v1, v0, s[86:87]
.Ltp3_L0_f_b4:
	s_mov_b64 exec, s[6:7]
	s_waitcnt vmcnt(51)
	v_mfma_f32_32x32x16_bf16 v[0:15], v[16:19], v[76:79], 0
	s_waitcnt vmcnt(50)
	v_mfma_f32_32x32x16_bf16 v[0:15], v[20:23], v[68:71], v[0:15]
	s_waitcnt vmcnt(49)
	v_mfma_f32_32x32x16_bf16 v[0:15], v[24:27], v[56:59], v[0:15]
	s_waitcnt vmcnt(48)
	v_mfma_f32_32x32x16_bf16 v[0:15], v[28:31], v[48:51], v[0:15]
	global_load_dwordx4 v[76:79], v185, s[98:99]
	global_load_dwordx4 v[68:71], v185, s[98:99] offset:1024
	global_load_dwordx4 v[56:59], v185, s[98:99] offset:2048
	global_load_dwordx4 v[48:51], v185, s[98:99] offset:3072
	s_and_saveexec_b64 s[6:7], s[0:1]
	s_cbranch_execz .Ltp3_L0_f_a5
	s_nop 9
	v_add_u32_e32 v4, 0xa0, v148
	v_cvt_f32_i32_e32 v4, v4
	v_mul_f32_e32 v4, 0xb9000400, v4
	v_mul_f32_e64 v5, |v144|, v4
	v_mul_f32_e64 v4, |v147|, v4
	v_mul_f32_e32 v5, 0x3fb8aa3b, v5
	v_mul_f32_e32 v4, 0x3fb8aa3b, v4
	v_exp_f32_e32 v5, v5
	v_exp_f32_e32 v4, v4
	v_mul_f32_e32 v0, v5, v0
	v_mul_f32_e32 v1, v4, v1
	v_mul_f32_e32 v2, v5, v2
	ds_write_b32 v157, v0 offset:640
	ds_write_b32 v156, v1 offset:64892
	v_add_u32_e32 v0, 0x10280, v157
	ds_write_b32 v0, v2
	v_mul_f32_e32 v0, v4, v3
	v_add_u32_e32 v1, 0x1fd7c, v156
	ds_write_b32 v1, v0
.Ltp3_L0_f_a5:
	s_or_b64 exec, exec, s[6:7]
	s_mov_b64 s[6:7], exec
	s_andn2_b64 exec, exec, s[0:1]
	s_cbranch_execz .Ltp3_L0_f_b5
	s_nop 9
	v_add_u32_e32 v4, 0xa0, v148
	v_cvt_f32_i32_e32 v4, v4
	v_mul_f32_e32 v4, 0xb9000400, v4
	v_mul_f32_e64 v5, |v144|, v4
	v_mul_f32_e64 v4, |v147|, v4
	v_mul_f32_e32 v5, 0x3fb8aa3b, v5
	v_mul_f32_e32 v4, 0x3fb8aa3b, v4
	v_exp_f32_e32 v5, v5
	v_exp_f32_e32 v4, v4
	v_mul_f32_e32 v0, v5, v0
	v_mul_f32_e32 v1, v4, v1
	v_mul_f32_e32 v2, v5, v2
	global_store_dword v189, v0, s[86:87] offset:640
	global_store_dword v191, v1, s[86:87] offset:3452
	v_add_u32_e32 v0, 0x10280, v189
	global_store_dword v0, v2, s[86:87]
	v_mul_f32_e32 v0, v4, v3
	v_add_u32_e32 v1, 0x1fd7c, v190
	global_store_dword v1, v0, s[86:87]
.Ltp3_L0_f_b5:
	s_mov_b64 exec, s[6:7]
	s_waitcnt vmcnt(55)
	v_mfma_f32_32x32x16_bf16 v[0:15], v[16:19], v[72:75], 0
	s_waitcnt vmcnt(54)
	v_mfma_f32_32x32x16_bf16 v[0:15], v[20:23], v[60:63], v[0:15]
	s_waitcnt vmcnt(53)
	v_mfma_f32_32x32x16_bf16 v[0:15], v[24:27], v[64:67], v[0:15]
	s_waitcnt vmcnt(52)
	v_mfma_f32_32x32x16_bf16 v[0:15], v[28:31], v[52:55], v[0:15]
	global_load_dwordx4 v[72:75], v186, s[98:99]
	global_load_dwordx4 v[60:63], v186, s[98:99] offset:1024
	global_load_dwordx4 v[64:67], v186, s[98:99] offset:2048
	global_load_dwordx4 v[52:55], v186, s[98:99] offset:3072
	s_and_saveexec_b64 s[6:7], s[0:1]
	s_cbranch_execz .Ltp3_L0_f_a6
	s_nop 9
	v_add_u32_e32 v4, 0xc0, v148
	v_cvt_f32_i32_e32 v4, v4
	v_mul_f32_e32 v4, 0xb9000400, v4
	v_mul_f32_e64 v5, |v144|, v4
	v_mul_f32_e64 v4, |v147|, v4
	v_mul_f32_e32 v5, 0x3fb8aa3b, v5
	v_mul_f32_e32 v4, 0x3fb8aa3b, v4
	v_exp_f32_e32 v5, v5
	v_exp_f32_e32 v4, v4
	v_mul_f32_e32 v0, v5, v0
	v_mul_f32_e32 v1, v4, v1
	v_mul_f32_e32 v2, v5, v2
	ds_write_b32 v157, v0 offset:768
	ds_write_b32 v156, v1 offset:64764
	v_add_u32_e32 v0, 0x10300, v157
	ds_write_b32 v0, v2
	v_mul_f32_e32 v0, v4, v3
	v_add_u32_e32 v1, 0x1fcfc, v156
	ds_write_b32 v1, v0
.Ltp3_L0_f_a6:
	s_or_b64 exec, exec, s[6:7]
	s_mov_b64 s[6:7], exec
	s_andn2_b64 exec, exec, s[0:1]
	s_cbranch_execz .Ltp3_L0_f_b6
	s_nop 9
	v_add_u32_e32 v4, 0xc0, v148
	v_cvt_f32_i32_e32 v4, v4
	v_mul_f32_e32 v4, 0xb9000400, v4
	v_mul_f32_e64 v5, |v144|, v4
	v_mul_f32_e64 v4, |v147|, v4
	v_mul_f32_e32 v5, 0x3fb8aa3b, v5
	v_mul_f32_e32 v4, 0x3fb8aa3b, v4
	v_exp_f32_e32 v5, v5
	v_exp_f32_e32 v4, v4
	v_mul_f32_e32 v0, v5, v0
	v_mul_f32_e32 v1, v4, v1
	v_mul_f32_e32 v2, v5, v2
	global_store_dword v189, v0, s[86:87] offset:768
	global_store_dword v191, v1, s[86:87] offset:3324
	v_add_u32_e32 v0, 0x10300, v189
	global_store_dword v0, v2, s[86:87]
	v_mul_f32_e32 v0, v4, v3
	v_add_u32_e32 v1, 0x1fcfc, v190
	global_store_dword v1, v0, s[86:87]
.Ltp3_L0_f_b6:
	s_mov_b64 exec, s[6:7]
	s_waitcnt vmcnt(59)
	v_mfma_f32_32x32x16_bf16 v[0:15], v[16:19], v[36:39], 0
	s_waitcnt vmcnt(58)
	v_mfma_f32_32x32x16_bf16 v[0:15], v[20:23], v[32:35], v[0:15]
	s_waitcnt vmcnt(57)
	v_mfma_f32_32x32x16_bf16 v[0:15], v[24:27], v[40:43], v[0:15]
	s_waitcnt vmcnt(56)
	v_mfma_f32_32x32x16_bf16 v[0:15], v[28:31], v[44:47], v[0:15]
	global_load_dwordx4 v[36:39], v187, s[98:99]
	global_load_dwordx4 v[32:35], v187, s[98:99] offset:1024
	global_load_dwordx4 v[40:43], v187, s[98:99] offset:2048
	global_load_dwordx4 v[44:47], v187, s[98:99] offset:3072
	s_and_saveexec_b64 s[6:7], s[0:1]
	s_cbranch_execz .Ltp3_L0_f_a7
	s_nop 9
	v_add_u32_e32 v4, 0xe0, v148
	v_cvt_f32_i32_e32 v4, v4
	s_movk_i32 s8, 0x1f1f
	v_cmp_ne_u32_e32 vcc, s8, v148
	v_mul_f32_e32 v4, 0xb9000400, v4
	v_mul_f32_e64 v5, |v144|, v4
	v_mul_f32_e64 v4, |v147|, v4
	v_mul_f32_e32 v5, 0x3fb8aa3b, v5
	v_mul_f32_e32 v4, 0x3fb8aa3b, v4
	v_exp_f32_e32 v4, v4
	v_exp_f32_e32 v5, v5
	v_cndmask_b32_e32 v4, 0, v4, vcc
	v_mul_f32_e32 v0, v5, v0
	ds_write_b32 v157, v0 offset:896
	v_mul_f32_e32 v0, v4, v1
	ds_write_b32 v156, v0 offset:64636
	v_mul_f32_e32 v0, v5, v2
	v_add_u32_e32 v1, 0x10380, v157
	ds_write_b32 v1, v0
	v_mul_f32_e32 v0, v4, v3
	v_add_u32_e32 v1, 0x1fc7c, v156
	ds_write_b32 v1, v0
.Ltp3_L0_f_a7:
	s_or_b64 exec, exec, s[6:7]
	s_mov_b64 s[6:7], exec
	s_andn2_b64 exec, exec, s[0:1]
	s_cbranch_execz .Ltp3_L0_f_b7
	s_nop 9
	v_add_u32_e32 v4, 0xe0, v148
	v_cvt_f32_i32_e32 v4, v4
	s_movk_i32 s8, 0x1f1f
	v_cmp_ne_u32_e32 vcc, s8, v148
	v_mul_f32_e32 v4, 0xb9000400, v4
	v_mul_f32_e64 v5, |v144|, v4
	v_mul_f32_e64 v4, |v147|, v4
	v_mul_f32_e32 v5, 0x3fb8aa3b, v5
	v_mul_f32_e32 v4, 0x3fb8aa3b, v4
	v_exp_f32_e32 v4, v4
	v_exp_f32_e32 v5, v5
	v_cndmask_b32_e32 v4, 0, v4, vcc
	v_mul_f32_e32 v0, v5, v0
	global_store_dword v189, v0, s[86:87] offset:896
	v_mul_f32_e32 v0, v4, v1
	global_store_dword v191, v0, s[86:87] offset:3196
	v_mul_f32_e32 v0, v5, v2
	v_add_u32_e32 v1, 0x10380, v189
	global_store_dword v1, v0, s[86:87]
	v_mul_f32_e32 v0, v4, v3
	v_add_u32_e32 v1, 0x1fc7c, v190
	global_store_dword v1, v0, s[86:87]
.Ltp3_L0_f_b7:
	s_mov_b64 exec, s[6:7]
	v_add_u32_e32 v149, 0x400, v149
	v_add_u32_e32 v155, 0xfffffc00, v155
	v_add_u32_e32 v148, 0x100, v148
	s_mov_b32 s4, 0
.Ltp3_loop_L0:
	s_add_u32 s98, s98, 0x8000
	s_addc_u32 s99, s99, 0
	v_add_u32_e32 v157, 16, v149
	v_add_u32_e32 v156, 16, v155
	v_add_u32_e32 v189, v188, v149
	v_add_u32_e32 v190, v188, v155
	v_add_u32_e32 v191, 0xf000, v190
	s_waitcnt vmcnt(63)
	v_mfma_f32_32x32x16_bf16 v[0:15], v[16:19], v[164:167], 0
	s_waitcnt vmcnt(62)
	v_mfma_f32_32x32x16_bf16 v[0:15], v[20:23], v[168:171], v[0:15]
	s_waitcnt vmcnt(61)
	v_mfma_f32_32x32x16_bf16 v[0:15], v[24:27], v[172:175], v[0:15]
	s_waitcnt vmcnt(60)
	v_mfma_f32_32x32x16_bf16 v[0:15], v[28:31], v[176:179], v[0:15]
	global_load_dwordx4 v[164:167], v180, s[98:99]
	global_load_dwordx4 v[168:171], v180, s[98:99] offset:1024
	global_load_dwordx4 v[172:175], v180, s[98:99] offset:2048
	global_load_dwordx4 v[176:179], v180, s[98:99] offset:3072
	s_and_saveexec_b64 s[6:7], s[0:1]
	s_cbranch_execz .Ltp3_L0_m_a0
	s_nop 7
	v_cvt_f32_i32_e32 v4, v148
	v_mul_f32_e32 v4, 0xb9000400, v4
	v_mul_f32_e64 v5, |v144|, v4
	v_mul_f32_e64 v4, |v147|, v4
	v_mul_f32_e32 v5, 0x3fb8aa3b, v5
	v_mul_f32_e32 v4, 0x3fb8aa3b, v4
	v_exp_f32_e32 v5, v5
	v_exp_f32_e32 v4, v4
	v_mul_f32_e32 v0, v5, v0
	v_mul_f32_e32 v1, v4, v1
	v_mul_f32_e32 v2, v5, v2
	ds_write_b32 v157, v0
	ds_write_b32 v156, v1 offset:65532
	v_add_u32_e32 v0, 0x10000, v157
	ds_write_b32 v0, v2
	v_mul_f32_e32 v0, v4, v3
	v_add_u32_e32 v1, 0x1fffc, v156
	ds_write_b32 v1, v0

.Ltp3_L0_m_b0:
	s_mov_b64 exec, s[6:7]
	s_waitcnt vmcnt(63)
	v_mfma_f32_32x32x16_bf16 v[0:15], v[16:19], v[140:143], 0
	s_waitcnt vmcnt(62)
	v_mfma_f32_32x32x16_bf16 v[0:15], v[20:23], v[136:139], v[0:15]
	s_waitcnt vmcnt(61)
	v_mfma_f32_32x32x16_bf16 v[0:15], v[24:27], v[132:135], v[0:15]
	s_waitcnt vmcnt(60)
	v_mfma_f32_32x32x16_bf16 v[0:15], v[28:31], v[128:131], v[0:15]
	global_load_dwordx4 v[140:143], v181, s[98:99]
	global_load_dwordx4 v[136:139], v181, s[98:99] offset:1024
	global_load_dwordx4 v[132:135], v181, s[98:99] offset:2048
	global_load_dwordx4 v[128:131], v181, s[98:99] offset:3072
	s_and_saveexec_b64 s[6:7], s[0:1]
	s_cbranch_execz .Ltp3_L0_m_a1
	s_nop 9
	v_add_u32_e32 v4, 32, v148
	v_cvt_f32_i32_e32 v4, v4
	v_mul_f32_e32 v4, 0xb9000400, v4
	v_mul_f32_e64 v5, |v144|, v4
	v_mul_f32_e64 v4, |v147|, v4
	v_mul_f32_e32 v5, 0x3fb8aa3b, v5
	v_mul_f32_e32 v4, 0x3fb8aa3b, v4
	v_exp_f32_e32 v5, v5
	v_exp_f32_e32 v4, v4
	v_mul_f32_e32 v0, v5, v0
	v_mul_f32_e32 v1, v4, v1
	v_mul_f32_e32 v2, v5, v2
	ds_write_b32 v157, v0 offset:128
	ds_write_b32 v156, v1 offset:65404
	v_add_u32_e32 v0, 0x10080, v157
	ds_write_b32 v0, v2
	v_mul_f32_e32 v0, v4, v3
	v_add_u32_e32 v1, 0x1ff7c, v156
	ds_write_b32 v1, v0

.Ltp3_L0_m_b1:
	s_mov_b64 exec, s[6:7]
	s_waitcnt vmcnt(63)
	v_mfma_f32_32x32x16_bf16 v[0:15], v[16:19], v[124:127], 0
	s_waitcnt vmcnt(62)
	v_mfma_f32_32x32x16_bf16 v[0:15], v[20:23], v[120:123], v[0:15]
	s_waitcnt vmcnt(61)
	v_mfma_f32_32x32x16_bf16 v[0:15], v[24:27], v[116:119], v[0:15]
	s_waitcnt vmcnt(60)
	v_mfma_f32_32x32x16_bf16 v[0:15], v[28:31], v[112:115], v[0:15]
	global_load_dwordx4 v[124:127], v182, s[98:99]
	global_load_dwordx4 v[120:123], v182, s[98:99] offset:1024
	global_load_dwordx4 v[116:119], v182, s[98:99] offset:2048
	global_load_dwordx4 v[112:115], v182, s[98:99] offset:3072
	s_and_saveexec_b64 s[6:7], s[0:1]
	s_cbranch_execz .Ltp3_L0_m_a2
	s_nop 9
	v_add_u32_e32 v4, 64, v148
	v_cvt_f32_i32_e32 v4, v4
	v_mul_f32_e32 v4, 0xb9000400, v4
	v_mul_f32_e64 v5, |v144|, v4
	v_mul_f32_e64 v4, |v147|, v4
	v_mul_f32_e32 v5, 0x3fb8aa3b, v5
	v_mul_f32_e32 v4, 0x3fb8aa3b, v4
	v_exp_f32_e32 v5, v5
	v_exp_f32_e32 v4, v4
	v_mul_f32_e32 v0, v5, v0
	v_mul_f32_e32 v1, v4, v1
	v_mul_f32_e32 v2, v5, v2
	ds_write_b32 v157, v0 offset:256
	ds_write_b32 v156, v1 offset:65276
	v_add_u32_e32 v0, 0x10100, v157
	ds_write_b32 v0, v2
	v_mul_f32_e32 v0, v4, v3
	v_add_u32_e32 v1, 0x1fefc, v156
	ds_write_b32 v1, v0

.Ltp3_L0_m_b2:
	s_mov_b64 exec, s[6:7]
	s_waitcnt vmcnt(63)
	v_mfma_f32_32x32x16_bf16 v[0:15], v[16:19], v[108:111], 0
	s_waitcnt vmcnt(62)
	v_mfma_f32_32x32x16_bf16 v[0:15], v[20:23], v[104:107], v[0:15]
	s_waitcnt vmcnt(61)
	v_mfma_f32_32x32x16_bf16 v[0:15], v[24:27], v[100:103], v[0:15]
	s_waitcnt vmcnt(60)
	v_mfma_f32_32x32x16_bf16 v[0:15], v[28:31], v[96:99], v[0:15]
	global_load_dwordx4 v[108:111], v183, s[98:99]
	global_load_dwordx4 v[104:107], v183, s[98:99] offset:1024
	global_load_dwordx4 v[100:103], v183, s[98:99] offset:2048
	global_load_dwordx4 v[96:99], v183, s[98:99] offset:3072
	s_and_saveexec_b64 s[6:7], s[0:1]
	s_cbranch_execz .Ltp3_L0_m_a3
	s_nop 9
	v_add_u32_e32 v4, 0x60, v148
	v_cvt_f32_i32_e32 v4, v4
	v_mul_f32_e32 v4, 0xb9000400, v4
	v_mul_f32_e64 v5, |v144|, v4
	v_mul_f32_e64 v4, |v147|, v4
	v_mul_f32_e32 v5, 0x3fb8aa3b, v5
	v_mul_f32_e32 v4, 0x3fb8aa3b, v4
	v_exp_f32_e32 v5, v5
	v_exp_f32_e32 v4, v4
	v_mul_f32_e32 v0, v5, v0
	v_mul_f32_e32 v1, v4, v1
	v_mul_f32_e32 v2, v5, v2
	ds_write_b32 v157, v0 offset:384
	ds_write_b32 v156, v1 offset:65148
	v_add_u32_e32 v0, 0x10180, v157
	ds_write_b32 v0, v2
	v_mul_f32_e32 v0, v4, v3
	v_add_u32_e32 v1, 0x1fe7c, v156
	ds_write_b32 v1, v0

.Ltp3_L0_m_b3:
	s_mov_b64 exec, s[6:7]
	s_waitcnt vmcnt(63)
	v_mfma_f32_32x32x16_bf16 v[0:15], v[16:19], v[92:95], 0
	s_waitcnt vmcnt(62)
	v_mfma_f32_32x32x16_bf16 v[0:15], v[20:23], v[88:91], v[0:15]
	s_waitcnt vmcnt(61)
	v_mfma_f32_32x32x16_bf16 v[0:15], v[24:27], v[84:87], v[0:15]
	s_waitcnt vmcnt(60)
	v_mfma_f32_32x32x16_bf16 v[0:15], v[28:31], v[80:83], v[0:15]
	global_load_dwordx4 v[92:95], v184, s[98:99]
	global_load_dwordx4 v[88:91], v184, s[98:99] offset:1024
	global_load_dwordx4 v[84:87], v184, s[98:99] offset:2048
	global_load_dwordx4 v[80:83], v184, s[98:99] offset:3072
	s_and_saveexec_b64 s[6:7], s[0:1]
	s_cbranch_execz .Ltp3_L0_m_a4
	s_nop 9
	v_add_u32_e32 v4, 0x80, v148
	v_cvt_f32_i32_e32 v4, v4
	v_mul_f32_e32 v4, 0xb9000400, v4
	v_mul_f32_e64 v5, |v144|, v4
	v_mul_f32_e64 v4, |v147|, v4
	v_mul_f32_e32 v5, 0x3fb8aa3b, v5
	v_mul_f32_e32 v4, 0x3fb8aa3b, v4
	v_exp_f32_e32 v5, v5
	v_exp_f32_e32 v4, v4
	v_mul_f32_e32 v0, v5, v0
	v_mul_f32_e32 v1, v4, v1
	v_mul_f32_e32 v2, v5, v2
	ds_write_b32 v157, v0 offset:512
	ds_write_b32 v156, v1 offset:65020
	v_add_u32_e32 v0, 0x10200, v157
	ds_write_b32 v0, v2
	v_mul_f32_e32 v0, v4, v3
	v_add_u32_e32 v1, 0x1fdfc, v156
	ds_write_b32 v1, v0

.Ltp3_L0_m_b4:
	s_mov_b64 exec, s[6:7]
	s_waitcnt vmcnt(63)
	v_mfma_f32_32x32x16_bf16 v[0:15], v[16:19], v[76:79], 0
	s_waitcnt vmcnt(62)
	v_mfma_f32_32x32x16_bf16 v[0:15], v[20:23], v[68:71], v[0:15]
	s_waitcnt vmcnt(61)
	v_mfma_f32_32x32x16_bf16 v[0:15], v[24:27], v[56:59], v[0:15]
	s_waitcnt vmcnt(60)
	v_mfma_f32_32x32x16_bf16 v[0:15], v[28:31], v[48:51], v[0:15]
	global_load_dwordx4 v[76:79], v185, s[98:99]
	global_load_dwordx4 v[68:71], v185, s[98:99] offset:1024
	global_load_dwordx4 v[56:59], v185, s[98:99] offset:2048
	global_load_dwordx4 v[48:51], v185, s[98:99] offset:3072
	s_and_saveexec_b64 s[6:7], s[0:1]
	s_cbranch_execz .Ltp3_L0_m_a5
	s_nop 9
	v_add_u32_e32 v4, 0xa0, v148
	v_cvt_f32_i32_e32 v4, v4
	v_mul_f32_e32 v4, 0xb9000400, v4
	v_mul_f32_e64 v5, |v144|, v4
	v_mul_f32_e64 v4, |v147|, v4
	v_mul_f32_e32 v5, 0x3fb8aa3b, v5
	v_mul_f32_e32 v4, 0x3fb8aa3b, v4
	v_exp_f32_e32 v5, v5
	v_exp_f32_e32 v4, v4
	v_mul_f32_e32 v0, v5, v0
	v_mul_f32_e32 v1, v4, v1
	v_mul_f32_e32 v2, v5, v2
	ds_write_b32 v157, v0 offset:640
	ds_write_b32 v156, v1 offset:64892
	v_add_u32_e32 v0, 0x10280, v157
	ds_write_b32 v0, v2
	v_mul_f32_e32 v0, v4, v3
	v_add_u32_e32 v1, 0x1fd7c, v156
	ds_write_b32 v1, v0

.Ltp3_L0_m_b5:
	s_mov_b64 exec, s[6:7]
	s_waitcnt vmcnt(63)
	v_mfma_f32_32x32x16_bf16 v[0:15], v[16:19], v[72:75], 0
	s_waitcnt vmcnt(62)
	v_mfma_f32_32x32x16_bf16 v[0:15], v[20:23], v[60:63], v[0:15]
	s_waitcnt vmcnt(61)
	v_mfma_f32_32x32x16_bf16 v[0:15], v[24:27], v[64:67], v[0:15]
	s_waitcnt vmcnt(60)
	v_mfma_f32_32x32x16_bf16 v[0:15], v[28:31], v[52:55], v[0:15]
	global_load_dwordx4 v[72:75], v186, s[98:99]
	global_load_dwordx4 v[60:63], v186, s[98:99] offset:1024
	global_load_dwordx4 v[64:67], v186, s[98:99] offset:2048
	global_load_dwordx4 v[52:55], v186, s[98:99] offset:3072
	s_and_saveexec_b64 s[6:7], s[0:1]
	s_cbranch_execz .Ltp3_L0_m_a6
	s_nop 9
	v_add_u32_e32 v4, 0xc0, v148
	v_cvt_f32_i32_e32 v4, v4
	v_mul_f32_e32 v4, 0xb9000400, v4
	v_mul_f32_e64 v5, |v144|, v4
	v_mul_f32_e64 v4, |v147|, v4
	v_mul_f32_e32 v5, 0x3fb8aa3b, v5
	v_mul_f32_e32 v4, 0x3fb8aa3b, v4
	v_exp_f32_e32 v5, v5
	v_exp_f32_e32 v4, v4
	v_mul_f32_e32 v0, v5, v0
	v_mul_f32_e32 v1, v4, v1
	v_mul_f32_e32 v2, v5, v2
	ds_write_b32 v157, v0 offset:768
	ds_write_b32 v156, v1 offset:64764
	v_add_u32_e32 v0, 0x10300, v157
	ds_write_b32 v0, v2
	v_mul_f32_e32 v0, v4, v3
	v_add_u32_e32 v1, 0x1fcfc, v156
	ds_write_b32 v1, v0

.Ltp3_L0_m_b6:
	s_mov_b64 exec, s[6:7]
	s_waitcnt vmcnt(63)
	v_mfma_f32_32x32x16_bf16 v[0:15], v[16:19], v[36:39], 0
	s_waitcnt vmcnt(62)
	v_mfma_f32_32x32x16_bf16 v[0:15], v[20:23], v[32:35], v[0:15]
	s_waitcnt vmcnt(61)
	v_mfma_f32_32x32x16_bf16 v[0:15], v[24:27], v[40:43], v[0:15]
	s_waitcnt vmcnt(60)
	v_mfma_f32_32x32x16_bf16 v[0:15], v[28:31], v[44:47], v[0:15]
	global_load_dwordx4 v[36:39], v187, s[98:99]
	global_load_dwordx4 v[32:35], v187, s[98:99] offset:1024
	global_load_dwordx4 v[40:43], v187, s[98:99] offset:2048
	global_load_dwordx4 v[44:47], v187, s[98:99] offset:3072
	s_and_saveexec_b64 s[6:7], s[0:1]
	s_cbranch_execz .Ltp3_L0_m_a7
	s_nop 9
	v_add_u32_e32 v4, 0xe0, v148
	v_cvt_f32_i32_e32 v4, v4
	s_movk_i32 s8, 0x1f1f
	v_cmp_ne_u32_e32 vcc, s8, v148
	v_mul_f32_e32 v4, 0xb9000400, v4
	v_mul_f32_e64 v5, |v144|, v4
	v_mul_f32_e64 v4, |v147|, v4
	v_mul_f32_e32 v5, 0x3fb8aa3b, v5
	v_mul_f32_e32 v4, 0x3fb8aa3b, v4
	v_exp_f32_e32 v4, v4
	v_exp_f32_e32 v5, v5
	v_cndmask_b32_e32 v4, 0, v4, vcc
	v_mul_f32_e32 v0, v5, v0
	ds_write_b32 v157, v0 offset:896
	v_mul_f32_e32 v0, v4, v1
	ds_write_b32 v156, v0 offset:64636
	v_mul_f32_e32 v0, v5, v2
	v_add_u32_e32 v1, 0x10380, v157
	ds_write_b32 v1, v0
	v_mul_f32_e32 v0, v4, v3
	v_add_u32_e32 v1, 0x1fc7c, v156
	ds_write_b32 v1, v0

.Ltp3_L0_m_b7:
	s_mov_b64 exec, s[6:7]
	v_add_u32_e32 v149, 0x400, v149
	v_add_u32_e32 v155, 0xfffffc00, v155
	v_add_u32_e32 v148, 0x100, v148
	s_add_i32 s4, s4, 1
	s_cmp_lt_u32 s4, 2
	s_cbranch_scc1 .Ltp3_loop_L0
	v_add_u32_e32 v157, 16, v149
	v_add_u32_e32 v156, 16, v155
	v_add_u32_e32 v189, v188, v149
	v_add_u32_e32 v190, v188, v155
	v_add_u32_e32 v191, 0xf000, v190
	s_waitcnt vmcnt(63)
	v_mfma_f32_32x32x16_bf16 v[0:15], v[16:19], v[164:167], 0
	s_waitcnt vmcnt(62)
	v_mfma_f32_32x32x16_bf16 v[0:15], v[20:23], v[168:171], v[0:15]
	s_waitcnt vmcnt(61)
	v_mfma_f32_32x32x16_bf16 v[0:15], v[24:27], v[172:175], v[0:15]
	s_waitcnt vmcnt(60)
	v_mfma_f32_32x32x16_bf16 v[0:15], v[28:31], v[176:179], v[0:15]
	s_and_saveexec_b64 s[6:7], s[0:1]
	s_cbranch_execz .Ltp3_L0_l_a0
	s_nop 7
	v_cvt_f32_i32_e32 v4, v148
	v_mul_f32_e32 v4, 0xb9000400, v4
	v_mul_f32_e64 v5, |v144|, v4
	v_mul_f32_e64 v4, |v147|, v4
	v_mul_f32_e32 v5, 0x3fb8aa3b, v5
	v_mul_f32_e32 v4, 0x3fb8aa3b, v4
	v_exp_f32_e32 v5, v5
	v_exp_f32_e32 v4, v4
	v_mul_f32_e32 v0, v5, v0
	v_mul_f32_e32 v1, v4, v1
	v_mul_f32_e32 v2, v5, v2
	ds_write_b32 v157, v0
	ds_write_b32 v156, v1 offset:65532
	v_add_u32_e32 v0, 0x10000, v157
	ds_write_b32 v0, v2
	v_mul_f32_e32 v0, v4, v3
	v_add_u32_e32 v1, 0x1fffc, v156
	ds_write_b32 v1, v0

.Ltp3_L0_l_b0:
	s_mov_b64 exec, s[6:7]
	s_waitcnt vmcnt(59)
	v_mfma_f32_32x32x16_bf16 v[0:15], v[16:19], v[140:143], 0
	s_waitcnt vmcnt(58)
	v_mfma_f32_32x32x16_bf16 v[0:15], v[20:23], v[136:139], v[0:15]
	s_waitcnt vmcnt(57)
	v_mfma_f32_32x32x16_bf16 v[0:15], v[24:27], v[132:135], v[0:15]
	s_waitcnt vmcnt(56)
	v_mfma_f32_32x32x16_bf16 v[0:15], v[28:31], v[128:131], v[0:15]
	s_and_saveexec_b64 s[6:7], s[0:1]
	s_cbranch_execz .Ltp3_L0_l_a1
	s_nop 9
	v_add_u32_e32 v4, 32, v148
	v_cvt_f32_i32_e32 v4, v4
	v_mul_f32_e32 v4, 0xb9000400, v4
	v_mul_f32_e64 v5, |v144|, v4
	v_mul_f32_e64 v4, |v147|, v4
	v_mul_f32_e32 v5, 0x3fb8aa3b, v5
	v_mul_f32_e32 v4, 0x3fb8aa3b, v4
	v_exp_f32_e32 v5, v5
	v_exp_f32_e32 v4, v4
	v_mul_f32_e32 v0, v5, v0
	v_mul_f32_e32 v1, v4, v1
	v_mul_f32_e32 v2, v5, v2
	ds_write_b32 v157, v0 offset:128
	ds_write_b32 v156, v1 offset:65404
	v_add_u32_e32 v0, 0x10080, v157
	ds_write_b32 v0, v2
	v_mul_f32_e32 v0, v4, v3
	v_add_u32_e32 v1, 0x1ff7c, v156
	ds_write_b32 v1, v0

.Ltp3_L0_l_b1:
	s_mov_b64 exec, s[6:7]
	s_waitcnt vmcnt(55)
	v_mfma_f32_32x32x16_bf16 v[0:15], v[16:19], v[124:127], 0
	s_waitcnt vmcnt(54)
	v_mfma_f32_32x32x16_bf16 v[0:15], v[20:23], v[120:123], v[0:15]
	s_waitcnt vmcnt(53)
	v_mfma_f32_32x32x16_bf16 v[0:15], v[24:27], v[116:119], v[0:15]
	s_waitcnt vmcnt(52)
	v_mfma_f32_32x32x16_bf16 v[0:15], v[28:31], v[112:115], v[0:15]
	s_and_saveexec_b64 s[6:7], s[0:1]
	s_cbranch_execz .Ltp3_L0_l_a2
	s_nop 9
	v_add_u32_e32 v4, 64, v148
	v_cvt_f32_i32_e32 v4, v4
	v_mul_f32_e32 v4, 0xb9000400, v4
	v_mul_f32_e64 v5, |v144|, v4
	v_mul_f32_e64 v4, |v147|, v4
	v_mul_f32_e32 v5, 0x3fb8aa3b, v5
	v_mul_f32_e32 v4, 0x3fb8aa3b, v4
	v_exp_f32_e32 v5, v5
	v_exp_f32_e32 v4, v4
	v_mul_f32_e32 v0, v5, v0
	v_mul_f32_e32 v1, v4, v1
	v_mul_f32_e32 v2, v5, v2
	ds_write_b32 v157, v0 offset:256
	ds_write_b32 v156, v1 offset:65276
	v_add_u32_e32 v0, 0x10100, v157
	ds_write_b32 v0, v2
	v_mul_f32_e32 v0, v4, v3
	v_add_u32_e32 v1, 0x1fefc, v156
	ds_write_b32 v1, v0

.Ltp3_L0_l_b2:
	s_mov_b64 exec, s[6:7]
	s_waitcnt vmcnt(51)
	v_mfma_f32_32x32x16_bf16 v[0:15], v[16:19], v[108:111], 0
	s_waitcnt vmcnt(50)
	v_mfma_f32_32x32x16_bf16 v[0:15], v[20:23], v[104:107], v[0:15]
	s_waitcnt vmcnt(49)
	v_mfma_f32_32x32x16_bf16 v[0:15], v[24:27], v[100:103], v[0:15]
	s_waitcnt vmcnt(48)
	v_mfma_f32_32x32x16_bf16 v[0:15], v[28:31], v[96:99], v[0:15]
	s_and_saveexec_b64 s[6:7], s[0:1]
	s_cbranch_execz .Ltp3_L0_l_a3
	s_nop 9
	v_add_u32_e32 v4, 0x60, v148
	v_cvt_f32_i32_e32 v4, v4
	v_mul_f32_e32 v4, 0xb9000400, v4
	v_mul_f32_e64 v5, |v144|, v4
	v_mul_f32_e64 v4, |v147|, v4
	v_mul_f32_e32 v5, 0x3fb8aa3b, v5
	v_mul_f32_e32 v4, 0x3fb8aa3b, v4
	v_exp_f32_e32 v5, v5
	v_exp_f32_e32 v4, v4
	v_mul_f32_e32 v0, v5, v0
	v_mul_f32_e32 v1, v4, v1
	v_mul_f32_e32 v2, v5, v2
	ds_write_b32 v157, v0 offset:384
	ds_write_b32 v156, v1 offset:65148
	v_add_u32_e32 v0, 0x10180, v157
	ds_write_b32 v0, v2
	v_mul_f32_e32 v0, v4, v3
	v_add_u32_e32 v1, 0x1fe7c, v156
	ds_write_b32 v1, v0

.Ltp3_L0_l_b3:
	s_mov_b64 exec, s[6:7]
	s_waitcnt vmcnt(47)
	v_mfma_f32_32x32x16_bf16 v[0:15], v[16:19], v[92:95], 0
	s_waitcnt vmcnt(46)
	v_mfma_f32_32x32x16_bf16 v[0:15], v[20:23], v[88:91], v[0:15]
	s_waitcnt vmcnt(45)
	v_mfma_f32_32x32x16_bf16 v[0:15], v[24:27], v[84:87], v[0:15]
	s_waitcnt vmcnt(44)
	v_mfma_f32_32x32x16_bf16 v[0:15], v[28:31], v[80:83], v[0:15]
	s_and_saveexec_b64 s[6:7], s[0:1]
	s_cbranch_execz .Ltp3_L0_l_a4
	s_nop 9
	v_add_u32_e32 v4, 0x80, v148
	v_cvt_f32_i32_e32 v4, v4
	v_mul_f32_e32 v4, 0xb9000400, v4
	v_mul_f32_e64 v5, |v144|, v4
	v_mul_f32_e64 v4, |v147|, v4
	v_mul_f32_e32 v5, 0x3fb8aa3b, v5
	v_mul_f32_e32 v4, 0x3fb8aa3b, v4
	v_exp_f32_e32 v5, v5
	v_exp_f32_e32 v4, v4
	v_mul_f32_e32 v0, v5, v0
	v_mul_f32_e32 v1, v4, v1
	v_mul_f32_e32 v2, v5, v2
	ds_write_b32 v157, v0 offset:512
	ds_write_b32 v156, v1 offset:65020
	v_add_u32_e32 v0, 0x10200, v157
	ds_write_b32 v0, v2
	v_mul_f32_e32 v0, v4, v3
	v_add_u32_e32 v1, 0x1fdfc, v156
	ds_write_b32 v1, v0

.Ltp3_L0_l_b4:
	s_mov_b64 exec, s[6:7]
	s_waitcnt vmcnt(43)
	v_mfma_f32_32x32x16_bf16 v[0:15], v[16:19], v[76:79], 0
	s_waitcnt vmcnt(42)
	v_mfma_f32_32x32x16_bf16 v[0:15], v[20:23], v[68:71], v[0:15]
	s_waitcnt vmcnt(41)
	v_mfma_f32_32x32x16_bf16 v[0:15], v[24:27], v[56:59], v[0:15]
	s_waitcnt vmcnt(40)
	v_mfma_f32_32x32x16_bf16 v[0:15], v[28:31], v[48:51], v[0:15]
	s_and_saveexec_b64 s[6:7], s[0:1]
	s_cbranch_execz .Ltp3_L0_l_a5
	s_nop 9
	v_add_u32_e32 v4, 0xa0, v148
	v_cvt_f32_i32_e32 v4, v4
	v_mul_f32_e32 v4, 0xb9000400, v4
	v_mul_f32_e64 v5, |v144|, v4
	v_mul_f32_e64 v4, |v147|, v4
	v_mul_f32_e32 v5, 0x3fb8aa3b, v5
	v_mul_f32_e32 v4, 0x3fb8aa3b, v4
	v_exp_f32_e32 v5, v5
	v_exp_f32_e32 v4, v4
	v_mul_f32_e32 v0, v5, v0
	v_mul_f32_e32 v1, v4, v1
	v_mul_f32_e32 v2, v5, v2
	ds_write_b32 v157, v0 offset:640
	ds_write_b32 v156, v1 offset:64892
	v_add_u32_e32 v0, 0x10280, v157
	ds_write_b32 v0, v2
	v_mul_f32_e32 v0, v4, v3
	v_add_u32_e32 v1, 0x1fd7c, v156
	ds_write_b32 v1, v0

.Ltp3_L0_l_b5:
	s_mov_b64 exec, s[6:7]
	s_waitcnt vmcnt(39)
	v_mfma_f32_32x32x16_bf16 v[0:15], v[16:19], v[72:75], 0
	s_waitcnt vmcnt(38)
	v_mfma_f32_32x32x16_bf16 v[0:15], v[20:23], v[60:63], v[0:15]
	s_waitcnt vmcnt(37)
	v_mfma_f32_32x32x16_bf16 v[0:15], v[24:27], v[64:67], v[0:15]
	s_waitcnt vmcnt(36)
	v_mfma_f32_32x32x16_bf16 v[0:15], v[28:31], v[52:55], v[0:15]
	s_and_saveexec_b64 s[6:7], s[0:1]
	s_cbranch_execz .Ltp3_L0_l_a6
	s_nop 9
	v_add_u32_e32 v4, 0xc0, v148
	v_cvt_f32_i32_e32 v4, v4
	v_mul_f32_e32 v4, 0xb9000400, v4
	v_mul_f32_e64 v5, |v144|, v4
	v_mul_f32_e64 v4, |v147|, v4
	v_mul_f32_e32 v5, 0x3fb8aa3b, v5
	v_mul_f32_e32 v4, 0x3fb8aa3b, v4
	v_exp_f32_e32 v5, v5
	v_exp_f32_e32 v4, v4
	v_mul_f32_e32 v0, v5, v0
	v_mul_f32_e32 v1, v4, v1
	v_mul_f32_e32 v2, v5, v2
	ds_write_b32 v157, v0 offset:768
	ds_write_b32 v156, v1 offset:64764
	v_add_u32_e32 v0, 0x10300, v157
	ds_write_b32 v0, v2
	v_mul_f32_e32 v0, v4, v3
	v_add_u32_e32 v1, 0x1fcfc, v156
	ds_write_b32 v1, v0

.Ltp3_L0_l_b6:
	s_mov_b64 exec, s[6:7]
	s_waitcnt vmcnt(35)
	v_mfma_f32_32x32x16_bf16 v[0:15], v[16:19], v[36:39], 0
	s_waitcnt vmcnt(34)
	v_mfma_f32_32x32x16_bf16 v[0:15], v[20:23], v[32:35], v[0:15]
	s_waitcnt vmcnt(33)
	v_mfma_f32_32x32x16_bf16 v[0:15], v[24:27], v[40:43], v[0:15]
	s_waitcnt vmcnt(32)
	v_mfma_f32_32x32x16_bf16 v[0:15], v[28:31], v[44:47], v[0:15]
	s_and_saveexec_b64 s[6:7], s[0:1]
	s_cbranch_execz .Ltp3_L0_l_a7
	s_nop 9
	v_add_u32_e32 v4, 0xe0, v148
	v_cvt_f32_i32_e32 v4, v4
	s_movk_i32 s8, 0x1f1f
	v_cmp_ne_u32_e32 vcc, s8, v148
	v_mul_f32_e32 v4, 0xb9000400, v4
	v_mul_f32_e64 v5, |v144|, v4
	v_mul_f32_e64 v4, |v147|, v4
	v_mul_f32_e32 v5, 0x3fb8aa3b, v5
	v_mul_f32_e32 v4, 0x3fb8aa3b, v4
	v_exp_f32_e32 v4, v4
	v_exp_f32_e32 v5, v5
	v_cndmask_b32_e32 v4, 0, v4, vcc
	v_mul_f32_e32 v0, v5, v0
	ds_write_b32 v157, v0 offset:896
	v_mul_f32_e32 v0, v4, v1
	ds_write_b32 v156, v0 offset:64636
	v_mul_f32_e32 v0, v5, v2
	v_add_u32_e32 v1, 0x10380, v157
	ds_write_b32 v1, v0
	v_mul_f32_e32 v0, v4, v3
	v_add_u32_e32 v1, 0x1fc7c, v156
	ds_write_b32 v1, v0

.Ltp3_L0_l_b7:
	s_mov_b64 exec, s[6:7]
	v_add_u32_e32 v149, 0x400, v149
	v_add_u32_e32 v155, 0xfffffc00, v155
	v_add_u32_e32 v148, 0x100, v148
	s_branch .LBB0_536
.Ltp3_copy_L0:
	v_lshlrev_b32_e32 v32, 4, v146
	v_add_u32_e32 v33, s101, v32
	global_load_dwordx4 v[40:43], v33, s[86:87]
	v_add_u32_e32 v34, 0x2000, v33
	global_load_dwordx4 v[44:47], v34, s[86:87]
	v_add_u32_e32 v34, 0x4000, v33
	global_load_dwordx4 v[48:51], v34, s[86:87]
	v_add_u32_e32 v34, 0x6000, v33
	global_load_dwordx4 v[52:55], v34, s[86:87]
	v_add_u32_e32 v34, 0x8000, v33
	global_load_dwordx4 v[56:59], v34, s[86:87]
	v_add_u32_e32 v34, 0xa000, v33
	global_load_dwordx4 v[60:63], v34, s[86:87]
	v_add_u32_e32 v34, 0xc000, v33
	global_load_dwordx4 v[64:67], v34, s[86:87]
	v_add_u32_e32 v34, 0xe000, v33
	global_load_dwordx4 v[68:71], v34, s[86:87]
	v_add_u32_e32 v34, 0x10000, v33
	global_load_dwordx4 v[72:75], v34, s[86:87]
	v_add_u32_e32 v34, 0x12000, v33
	global_load_dwordx4 v[76:79], v34, s[86:87]
	v_add_u32_e32 v34, 0x14000, v33
	global_load_dwordx4 v[80:83], v34, s[86:87]
	v_add_u32_e32 v34, 0x16000, v33
	global_load_dwordx4 v[84:87], v34, s[86:87]
	v_add_u32_e32 v34, 0x18000, v33
	global_load_dwordx4 v[88:91], v34, s[86:87]
	v_add_u32_e32 v34, 0x1a000, v33
	global_load_dwordx4 v[92:95], v34, s[86:87]
	v_add_u32_e32 v34, 0x1c000, v33
	global_load_dwordx4 v[96:99], v34, s[86:87]
	v_add_u32_e32 v34, 0x1e000, v33
	global_load_dwordx4 v[100:103], v34, s[86:87]
	v_add_u32_e32 v32, 16, v32
	v_add_u32_e32 v35, 0x10000, v32
	s_waitcnt vmcnt(15)
	ds_write_b128 v32, v[40:43]
	s_waitcnt vmcnt(14)
	ds_write_b128 v32, v[44:47] offset:8192
	s_waitcnt vmcnt(13)
	ds_write_b128 v32, v[48:51] offset:16384
	s_waitcnt vmcnt(12)
	ds_write_b128 v32, v[52:55] offset:24576
	s_waitcnt vmcnt(11)
	ds_write_b128 v32, v[56:59] offset:32768
	s_waitcnt vmcnt(10)
	ds_write_b128 v32, v[60:63] offset:40960
	s_waitcnt vmcnt(9)
	ds_write_b128 v32, v[64:67] offset:49152
	s_waitcnt vmcnt(8)
	ds_write_b128 v32, v[68:71] offset:57344
	s_waitcnt vmcnt(7)
	ds_write_b128 v35, v[72:75]
	s_waitcnt vmcnt(6)
	ds_write_b128 v35, v[76:79] offset:8192
	s_waitcnt vmcnt(5)
	ds_write_b128 v35, v[80:83] offset:16384
	s_waitcnt vmcnt(4)
	ds_write_b128 v35, v[84:87] offset:24576
	s_waitcnt vmcnt(3)
	ds_write_b128 v35, v[88:91] offset:32768
	s_waitcnt vmcnt(2)
	ds_write_b128 v35, v[92:95] offset:40960
	s_waitcnt vmcnt(1)
	ds_write_b128 v35, v[96:99] offset:49152
	s_waitcnt vmcnt(0)
	ds_write_b128 v35, v[100:103] offset:57344
	s_waitcnt lgkmcnt(0)
	s_branch .LBB0_536

.LBB0_890:
	s_ashr_i32 s0, s29, 8
	v_readlane_b32 s1, v252, 56
	s_add_i32 s4, s1, s0
	v_readlane_b32 s0, v252, 40
	v_readlane_b32 s1, v252, 41
	v_mov_b32_e32 v146, v162
	s_and_b64 s[0:1], s[0:1], exec
	s_cselect_b32 s62, s4, s29
	v_mov_b32_e32 v32, v146
	s_barrier
	v_readlane_b32 s4, v252, 22
	v_lshlrev_b32_e32 v2, 11, v32
	v_and_b32_e32 v144, 0x1000, v2
	v_readlane_b32 s6, v252, 24
	v_readlane_b32 s7, v252, 25
	v_bfe_u32 v33, v32, 5, 1
	s_ashr_i32 s63, s62, 31
	v_lshl_add_u64 v[0:1], s[6:7], 0, v[144:145]
	v_and_b32_e32 v144, 0x800, v2
	v_lshl_add_u64 v[0:1], v[0:1], 0, v[144:145]
	v_lshl_add_u64 v[0:1], s[62:63], 2, v[0:1]
	v_and_b32_e32 v144, 4, v32
	v_lshl_add_u64 v[0:1], v[0:1], 0, v[144:145]
	v_lshlrev_b32_e32 v144, 16, v33
	v_lshl_add_u64 v[0:1], v[0:1], 0, v[144:145]
	s_mov_b32 s0, 0x80000
	v_add_co_u32_e32 v2, vcc, s0, v0
	s_mov_b32 s0, 0x82000
	s_nop 0
	v_addc_co_u32_e32 v3, vcc, 0, v1, vcc
	v_add_co_u32_e32 v4, vcc, s0, v0
	s_mov_b32 s0, 0x84000
	s_nop 0
	v_addc_co_u32_e32 v5, vcc, 0, v1, vcc
	v_add_co_u32_e32 v6, vcc, s0, v0
	s_mov_b32 s0, 0x86000
	s_nop 0
	v_addc_co_u32_e32 v7, vcc, 0, v1, vcc
	v_add_co_u32_e32 v8, vcc, s0, v0
	s_mov_b32 s0, 0x88000
	s_nop 0
	v_addc_co_u32_e32 v9, vcc, 0, v1, vcc
	v_add_co_u32_e32 v10, vcc, s0, v0
	s_mov_b32 s0, 0x8a000
	s_nop 0
	v_addc_co_u32_e32 v11, vcc, 0, v1, vcc
	v_add_co_u32_e32 v12, vcc, s0, v0
	s_mov_b32 s0, 0x8c000
	s_nop 0
	v_addc_co_u32_e32 v13, vcc, 0, v1, vcc
	v_add_co_u32_e32 v14, vcc, s0, v0
	s_mov_b32 s0, 0x8e000
	s_nop 0
	v_addc_co_u32_e32 v15, vcc, 0, v1, vcc
	v_add_co_u32_e32 v16, vcc, s0, v0
	s_mov_b32 s0, 0xa0000
	s_nop 0
	v_addc_co_u32_e32 v17, vcc, 0, v1, vcc
	global_load_dword v19, v[2:3], off
	global_load_dword v20, v[4:5], off
	global_load_dword v21, v[6:7], off
	global_load_dword v22, v[8:9], off
	global_load_dword v23, v[10:11], off
	global_load_dword v24, v[12:13], off
	global_load_dword v25, v[14:15], off
	global_load_dword v26, v[16:17], off
	v_add_co_u32_e32 v2, vcc, s0, v0
	s_mov_b32 s0, 0xa2000
	s_nop 0
	v_addc_co_u32_e32 v3, vcc, 0, v1, vcc
	v_add_co_u32_e32 v4, vcc, s0, v0
	s_mov_b32 s0, 0xa4000
	s_nop 0
	v_addc_co_u32_e32 v5, vcc, 0, v1, vcc
	v_add_co_u32_e32 v6, vcc, s0, v0
	s_mov_b32 s0, 0xa6000
	s_nop 0
	v_addc_co_u32_e32 v7, vcc, 0, v1, vcc
	v_add_co_u32_e32 v8, vcc, s0, v0
	s_mov_b32 s0, 0xa8000
	s_nop 0
	v_addc_co_u32_e32 v9, vcc, 0, v1, vcc
	v_add_co_u32_e32 v10, vcc, s0, v0
	s_mov_b32 s0, 0xaa000
	s_nop 0
	v_addc_co_u32_e32 v11, vcc, 0, v1, vcc
	v_add_co_u32_e32 v12, vcc, s0, v0
	s_mov_b32 s0, 0xac000
	s_nop 0
	v_addc_co_u32_e32 v13, vcc, 0, v1, vcc
	v_add_co_u32_e32 v14, vcc, s0, v0
	s_mov_b32 s0, 0xae000
	s_nop 0
	v_addc_co_u32_e32 v15, vcc, 0, v1, vcc
	v_add_co_u32_e32 v16, vcc, s0, v0
	s_mov_b32 s0, 0xc0000
	s_nop 0
	v_addc_co_u32_e32 v17, vcc, 0, v1, vcc
	global_load_dword v27, v[2:3], off
	global_load_dword v28, v[4:5], off
	global_load_dword v29, v[6:7], off
	global_load_dword v30, v[8:9], off
	global_load_dword v31, v[10:11], off
	global_load_dword v34, v[12:13], off
	global_load_dword v35, v[14:15], off
	global_load_dword v36, v[16:17], off
	v_add_co_u32_e32 v2, vcc, s0, v0
	s_mov_b32 s0, 0xc2000
	s_nop 0
	v_addc_co_u32_e32 v3, vcc, 0, v1, vcc
	v_add_co_u32_e32 v4, vcc, s0, v0
	s_mov_b32 s0, 0xc4000
	s_nop 0
	v_addc_co_u32_e32 v5, vcc, 0, v1, vcc
	v_add_co_u32_e32 v6, vcc, s0, v0
	s_mov_b32 s0, 0xc6000
	s_nop 0
	v_addc_co_u32_e32 v7, vcc, 0, v1, vcc
	v_add_co_u32_e32 v8, vcc, s0, v0
	s_mov_b32 s0, 0xc8000
	s_nop 0
	v_addc_co_u32_e32 v9, vcc, 0, v1, vcc
	v_add_co_u32_e32 v10, vcc, s0, v0
	s_mov_b32 s0, 0xca000
	s_nop 0
	v_addc_co_u32_e32 v11, vcc, 0, v1, vcc
	v_add_co_u32_e32 v12, vcc, s0, v0
	s_mov_b32 s0, 0xcc000
	s_nop 0
	v_addc_co_u32_e32 v13, vcc, 0, v1, vcc
	v_add_co_u32_e32 v14, vcc, s0, v0
	s_mov_b32 s0, 0xce000
	s_nop 0
	v_addc_co_u32_e32 v15, vcc, 0, v1, vcc
	v_add_co_u32_e32 v16, vcc, s0, v0
	s_mov_b32 s0, 0xe0000
	s_nop 0
	v_addc_co_u32_e32 v17, vcc, 0, v1, vcc
	global_load_dword v37, v[2:3], off
	global_load_dword v38, v[4:5], off
	global_load_dword v39, v[6:7], off
	global_load_dword v40, v[8:9], off
	global_load_dword v41, v[10:11], off
	global_load_dword v42, v[12:13], off
	global_load_dword v43, v[14:15], off
	global_load_dword v44, v[16:17], off
	v_add_co_u32_e32 v2, vcc, s0, v0
	s_mov_b32 s0, 0xe2000
	s_nop 0
	v_addc_co_u32_e32 v3, vcc, 0, v1, vcc
	v_add_co_u32_e32 v4, vcc, s0, v0
	s_mov_b32 s0, 0xe4000
	s_nop 0
	v_addc_co_u32_e32 v5, vcc, 0, v1, vcc
	v_add_co_u32_e32 v6, vcc, s0, v0
	s_mov_b32 s0, 0xe6000
	s_nop 0
	v_addc_co_u32_e32 v7, vcc, 0, v1, vcc
	v_add_co_u32_e32 v8, vcc, s0, v0
	s_mov_b32 s0, 0xe8000
	s_nop 0
	v_addc_co_u32_e32 v9, vcc, 0, v1, vcc
	v_add_co_u32_e32 v10, vcc, s0, v0
	s_mov_b32 s0, 0xea000
	s_nop 0
	v_addc_co_u32_e32 v11, vcc, 0, v1, vcc
	v_add_co_u32_e32 v12, vcc, s0, v0
	s_mov_b32 s0, 0xec000
	s_nop 0
	v_addc_co_u32_e32 v13, vcc, 0, v1, vcc
	v_add_co_u32_e32 v14, vcc, s0, v0
	s_mov_b32 s0, 0xee000
	s_nop 0
	v_addc_co_u32_e32 v15, vcc, 0, v1, vcc
	v_add_co_u32_e32 v0, vcc, s0, v0
	v_add_u32_e32 v18, s62, v33
	v_cvt_f32_i32_e32 v18, v18
	s_nop 0
	v_addc_co_u32_e32 v1, vcc, 0, v1, vcc
	global_load_dword v2, v[2:3], off
	s_nop 0
	global_load_dword v3, v[4:5], off
	s_nop 0
	global_load_dword v4, v[6:7], off
	global_load_dword v5, v[8:9], off
	s_nop 0
	global_load_dword v6, v[10:11], off
	global_load_dword v7, v[12:13], off
	global_load_dword v8, v[14:15], off
	s_nop 0
	global_load_dword v0, v[0:1], off
	s_mov_b32 s4, 0x43ff8000
	v_div_scale_f32 v1, s[0:1], s4, s4, v18
	v_rcp_f32_e32 v9, v1
	v_add_u32_e32 v13, s62, v33
	v_sub_u32_e32 v13, 0x1ff, v13
	v_cvt_f32_i32_e32 v13, v13
	v_readlane_b32 s5, v252, 23
	v_fma_f32 v10, -v1, v9, 1.0
	v_fmac_f32_e32 v9, v10, v9
	v_div_scale_f32 v10, vcc, v18, s4, v18
	v_mul_f32_e32 v11, v10, v9
	v_fma_f32 v12, -v1, v11, v10
	v_fmac_f32_e32 v11, v12, v9
	v_fma_f32 v1, -v1, v11, v10
	v_div_scale_f32 v10, s[0:1], s4, s4, v13
	v_rcp_f32_e32 v12, v10
	v_div_fmas_f32 v1, v1, v9, v11
	v_div_fixup_f32 v1, v1, s4, v18
	v_fmamk_f32 v144, v1, 0xc1447cbd, v150
	v_fma_f32 v1, -v10, v12, 1.0
	v_fmac_f32_e32 v12, v1, v12
	v_div_scale_f32 v1, vcc, v13, s4, v13
	v_mul_f32_e32 v9, v1, v12
	v_fma_f32 v11, -v10, v9, v1
	v_fmac_f32_e32 v9, v11, v12
	v_fma_f32 v1, -v10, v9, v1
	v_div_fmas_f32 v1, v1, v12, v9
	v_and_b32_e32 v9, 31, v32
	v_div_fixup_f32 v1, v1, s4, v13
	v_cmp_gt_u32_e32 vcc, 8, v9
	v_fmamk_f32 v147, v1, 0xc1447cbd, v150
	v_cmp_eq_u32_e64 s[0:1], 0, v33
	s_waitcnt vmcnt(31)
	v_cndmask_b32_e32 v1, 0, v19, vcc
	s_waitcnt vmcnt(30)
	v_cndmask_b32_e32 v10, 0, v20, vcc
	v_cvt_pk_bf16_f32 v16, v1, v10
	s_waitcnt vmcnt(23)
	v_cndmask_b32_e32 v1, 0, v27, vcc
	s_waitcnt vmcnt(22)
	v_cndmask_b32_e32 v10, 0, v28, vcc
	v_cvt_pk_bf16_f32 v20, v1, v10
	s_waitcnt vmcnt(15)
	v_cndmask_b32_e32 v1, 0, v37, vcc
	s_waitcnt vmcnt(14)
	v_cndmask_b32_e32 v10, 0, v38, vcc
	v_cndmask_b32_e32 v13, 0, v23, vcc
	v_cndmask_b32_e32 v14, 0, v24, vcc
	v_cvt_pk_bf16_f32 v24, v1, v10
	v_cvt_pk_bf16_f32 v18, v13, v14
	v_cndmask_b32_e32 v13, 0, v31, vcc
	v_cndmask_b32_e32 v11, 0, v21, vcc
	v_cndmask_b32_e32 v12, 0, v22, vcc
	v_cndmask_b32_e32 v15, 0, v25, vcc
	v_cndmask_b32_e32 v19, 0, v26, vcc
	v_cvt_pk_bf16_f32 v17, v11, v12
	v_cvt_pk_bf16_f32 v19, v15, v19
	v_cndmask_b32_e32 v11, 0, v29, vcc
	v_cndmask_b32_e32 v12, 0, v30, vcc
	v_cndmask_b32_e32 v14, 0, v34, vcc
	v_cndmask_b32_e32 v15, 0, v35, vcc
	v_cndmask_b32_e32 v23, 0, v36, vcc
	v_cvt_pk_bf16_f32 v21, v11, v12
	v_cvt_pk_bf16_f32 v22, v13, v14
	v_cvt_pk_bf16_f32 v23, v15, v23
	s_waitcnt vmcnt(13)
	v_cndmask_b32_e32 v11, 0, v39, vcc
	s_waitcnt vmcnt(12)
	v_cndmask_b32_e32 v12, 0, v40, vcc
	s_waitcnt vmcnt(11)
	v_cndmask_b32_e32 v13, 0, v41, vcc
	s_waitcnt vmcnt(10)
	v_cndmask_b32_e32 v14, 0, v42, vcc
	s_waitcnt vmcnt(9)
	v_cndmask_b32_e32 v15, 0, v43, vcc
	s_waitcnt vmcnt(8)
	v_cndmask_b32_e32 v27, 0, v44, vcc
	v_cvt_pk_bf16_f32 v25, v11, v12
	v_cvt_pk_bf16_f32 v26, v13, v14
	v_cvt_pk_bf16_f32 v27, v15, v27
	s_mov_b64 s[4:5], 0
	s_waitcnt vmcnt(7)
	v_cndmask_b32_e32 v1, 0, v2, vcc
	s_waitcnt vmcnt(6)
	v_cndmask_b32_e32 v2, 0, v3, vcc
	s_waitcnt vmcnt(5)
	v_cndmask_b32_e32 v3, 0, v4, vcc
	s_waitcnt vmcnt(4)
	v_cndmask_b32_e32 v4, 0, v5, vcc
	s_waitcnt vmcnt(3)
	v_cndmask_b32_e32 v5, 0, v6, vcc
	s_waitcnt vmcnt(2)
	v_cndmask_b32_e32 v6, 0, v7, vcc
	s_waitcnt vmcnt(1)
	v_cndmask_b32_e32 v7, 0, v8, vcc
	s_waitcnt vmcnt(0)
	v_cndmask_b32_e32 v0, 0, v0, vcc
	v_cvt_pk_bf16_f32 v31, v7, v0
	v_lshlrev_b32_e32 v0, 4, v32
	v_and_b32_e32 v0, 0xfffffc00, v0
	v_cvt_pk_bf16_f32 v28, v1, v2
	v_ashrrev_i32_e32 v1, 31, v0
	v_lshlrev_b32_e32 v2, 6, v32
	v_or_b32_e32 v155, v0, v9
	v_or_b32_e32 v0, v0, v9
	v_and_b32_e32 v2, 0xfffff000, v2
	v_lshlrev_b64 v[0:1], 7, v[0:1]
	v_lshl_or_b32 v153, v9, 2, v2
	v_lshl_or_b32 v0, v33, 4, v0
	v_cvt_pk_bf16_f32 v29, v3, v4
	v_cvt_pk_bf16_f32 v30, v5, v6
	v_sub_u32_e32 v154, 0, v153
	v_sub_u32_e32 v0, v155, v9
	v_lshlrev_b32_e32 v0, 7, v0
	v_lshl_add_u32 v0, v9, 4, v0
	v_lshl_add_u32 v0, v33, 9, v0
	v_mov_b32_e32 v1, 0
	v_lshl_add_u64 v[148:149], s[86:87], 0, v[0:1]
	v_readlane_b32 s8, v252, 26
	v_readlane_b32 s9, v252, 27
	v_readlane_b32 s10, v252, 28
	v_readlane_b32 s11, v252, 29
	v_readlane_b32 s12, v252, 30
	v_readlane_b32 s13, v252, 31
	v_readlane_b32 s14, v252, 32
	v_readlane_b32 s15, v252, 33
	v_readlane_b32 s16, v252, 34
	v_readlane_b32 s17, v252, 35
	v_readlane_b32 s18, v252, 36
	v_readlane_b32 s19, v252, 37
	s_branch .LBB0_892
.LBB0_892:
	s_mov_b32 s100, s29
	s_and_b32 s6, s100, 0xff
	s_lshl_b32 s101, s6, 17
	s_cmpk_ge_u32 s6, 0x80
	s_cselect_b32 s7, 0xb000000, 0
	s_add_u32 s101, s101, s7
	s_cmpk_ge_u32 s6, 0xd0
	s_cselect_b32 s7, 0x1000000, 0
	s_add_u32 s101, s101, s7
	s_cmpk_ge_u32 s100, 0x100
	s_cbranch_scc1 .Ltp3_copy_L1
	v_mov_b32_e32 v188, s101
	v_subrev_u32_e32 v180, s86, v148
	v_add_u32_e32 v181, 0x1000, v180
	v_add_u32_e32 v182, 0x2000, v180
	v_add_u32_e32 v183, 0x3000, v180
	v_add_u32_e32 v184, 0x4000, v180
	v_add_u32_e32 v185, 0x5000, v180
	v_add_u32_e32 v186, 0x6000, v180
	v_add_u32_e32 v187, 0x7000, v180
	s_add_u32 s98, s86, 0xe300000
	s_addc_u32 s99, s87, 0
	global_load_dwordx4 v[164:167], v180, s[98:99]
	global_load_dwordx4 v[168:171], v180, s[98:99] offset:1024
	global_load_dwordx4 v[172:175], v180, s[98:99] offset:2048
	global_load_dwordx4 v[176:179], v180, s[98:99] offset:3072
	global_load_dwordx4 v[140:143], v181, s[98:99]
	global_load_dwordx4 v[136:139], v181, s[98:99] offset:1024
	global_load_dwordx4 v[132:135], v181, s[98:99] offset:2048
	global_load_dwordx4 v[128:131], v181, s[98:99] offset:3072
	global_load_dwordx4 v[124:127], v182, s[98:99]
	global_load_dwordx4 v[120:123], v182, s[98:99] offset:1024
	global_load_dwordx4 v[116:119], v182, s[98:99] offset:2048
	global_load_dwordx4 v[112:115], v182, s[98:99] offset:3072
	global_load_dwordx4 v[108:111], v183, s[98:99]
	global_load_dwordx4 v[104:107], v183, s[98:99] offset:1024
	global_load_dwordx4 v[100:103], v183, s[98:99] offset:2048
	global_load_dwordx4 v[96:99], v183, s[98:99] offset:3072
	global_load_dwordx4 v[92:95], v184, s[98:99]
	global_load_dwordx4 v[88:91], v184, s[98:99] offset:1024
	global_load_dwordx4 v[84:87], v184, s[98:99] offset:2048
	global_load_dwordx4 v[80:83], v184, s[98:99] offset:3072
	global_load_dwordx4 v[76:79], v185, s[98:99]
	global_load_dwordx4 v[68:71], v185, s[98:99] offset:1024
	global_load_dwordx4 v[56:59], v185, s[98:99] offset:2048
	global_load_dwordx4 v[48:51], v185, s[98:99] offset:3072
	global_load_dwordx4 v[72:75], v186, s[98:99]
	global_load_dwordx4 v[60:63], v186, s[98:99] offset:1024
	global_load_dwordx4 v[64:67], v186, s[98:99] offset:2048
	global_load_dwordx4 v[52:55], v186, s[98:99] offset:3072
	global_load_dwordx4 v[36:39], v187, s[98:99]
	global_load_dwordx4 v[32:35], v187, s[98:99] offset:1024
	global_load_dwordx4 v[40:43], v187, s[98:99] offset:2048
	global_load_dwordx4 v[44:47], v187, s[98:99] offset:3072
	s_add_u32 s98, s98, 0x8000
	s_addc_u32 s99, s99, 0
	v_add_u32_e32 v157, 16, v153
	v_add_u32_e32 v156, 16, v154
	v_add_u32_e32 v189, v188, v153
	v_add_u32_e32 v190, v188, v154
	v_add_u32_e32 v191, 0xf000, v190
	s_waitcnt vmcnt(31)
	v_mfma_f32_32x32x16_bf16 v[0:15], v[16:19], v[164:167], 0
	s_waitcnt vmcnt(30)
	v_mfma_f32_32x32x16_bf16 v[0:15], v[20:23], v[168:171], v[0:15]
	s_waitcnt vmcnt(29)
	v_mfma_f32_32x32x16_bf16 v[0:15], v[24:27], v[172:175], v[0:15]
	s_waitcnt vmcnt(28)
	v_mfma_f32_32x32x16_bf16 v[0:15], v[28:31], v[176:179], v[0:15]
	global_load_dwordx4 v[164:167], v180, s[98:99]
	global_load_dwordx4 v[168:171], v180, s[98:99] offset:1024
	global_load_dwordx4 v[172:175], v180, s[98:99] offset:2048
	global_load_dwordx4 v[176:179], v180, s[98:99] offset:3072
	s_and_saveexec_b64 s[6:7], s[0:1]
	s_cbranch_execz .Ltp3_L1_f_a0
	s_nop 7
	v_cvt_f32_i32_e32 v4, v155
	v_mul_f32_e32 v4, 0xb9000400, v4
	v_mul_f32_e64 v5, |v144|, v4
	v_mul_f32_e64 v4, |v147|, v4
	v_mul_f32_e32 v5, 0x3fb8aa3b, v5
	v_mul_f32_e32 v4, 0x3fb8aa3b, v4
	v_exp_f32_e32 v5, v5
	v_exp_f32_e32 v4, v4
	v_mul_f32_e32 v0, v5, v0
	v_mul_f32_e32 v1, v4, v1
	v_mul_f32_e32 v2, v5, v2
	ds_write_b32 v157, v0
	ds_write_b32 v156, v1 offset:65532
	v_add_u32_e32 v0, 0x10000, v157
	ds_write_b32 v0, v2
	v_mul_f32_e32 v0, v4, v3
	v_add_u32_e32 v1, 0x1fffc, v156
	ds_write_b32 v1, v0
.Ltp3_L1_f_a0:
	s_or_b64 exec, exec, s[6:7]
	s_mov_b64 s[6:7], exec
	s_andn2_b64 exec, exec, s[0:1]
	s_cbranch_execz .Ltp3_L1_f_b0
	s_nop 7
	v_cvt_f32_i32_e32 v4, v155
	v_mul_f32_e32 v4, 0xb9000400, v4
	v_mul_f32_e64 v5, |v144|, v4
	v_mul_f32_e64 v4, |v147|, v4
	v_mul_f32_e32 v5, 0x3fb8aa3b, v5
	v_mul_f32_e32 v4, 0x3fb8aa3b, v4
	v_exp_f32_e32 v5, v5
	v_exp_f32_e32 v4, v4
	v_mul_f32_e32 v0, v5, v0
	v_mul_f32_e32 v1, v4, v1
	v_mul_f32_e32 v2, v5, v2
	global_store_dword v189, v0, s[86:87]
	global_store_dword v191, v1, s[86:87] offset:4092
	v_add_u32_e32 v0, 0x10000, v189
	global_store_dword v0, v2, s[86:87]
	v_mul_f32_e32 v0, v4, v3
	v_add_u32_e32 v1, 0x1fffc, v190
	global_store_dword v1, v0, s[86:87]
.Ltp3_L1_f_b0:
	s_mov_b64 exec, s[6:7]
	s_waitcnt vmcnt(35)
	v_mfma_f32_32x32x16_bf16 v[0:15], v[16:19], v[140:143], 0
	s_waitcnt vmcnt(34)
	v_mfma_f32_32x32x16_bf16 v[0:15], v[20:23], v[136:139], v[0:15]
	s_waitcnt vmcnt(33)
	v_mfma_f32_32x32x16_bf16 v[0:15], v[24:27], v[132:135], v[0:15]
	s_waitcnt vmcnt(32)
	v_mfma_f32_32x32x16_bf16 v[0:15], v[28:31], v[128:131], v[0:15]
	global_load_dwordx4 v[140:143], v181, s[98:99]
	global_load_dwordx4 v[136:139], v181, s[98:99] offset:1024
	global_load_dwordx4 v[132:135], v181, s[98:99] offset:2048
	global_load_dwordx4 v[128:131], v181, s[98:99] offset:3072
	s_and_saveexec_b64 s[6:7], s[0:1]
	s_cbranch_execz .Ltp3_L1_f_a1
	s_nop 9
	v_add_u32_e32 v4, 32, v155
	v_cvt_f32_i32_e32 v4, v4
	v_mul_f32_e32 v4, 0xb9000400, v4
	v_mul_f32_e64 v5, |v144|, v4
	v_mul_f32_e64 v4, |v147|, v4
	v_mul_f32_e32 v5, 0x3fb8aa3b, v5
	v_mul_f32_e32 v4, 0x3fb8aa3b, v4
	v_exp_f32_e32 v5, v5
	v_exp_f32_e32 v4, v4
	v_mul_f32_e32 v0, v5, v0
	v_mul_f32_e32 v1, v4, v1
	v_mul_f32_e32 v2, v5, v2
	ds_write_b32 v157, v0 offset:128
	ds_write_b32 v156, v1 offset:65404
	v_add_u32_e32 v0, 0x10080, v157
	ds_write_b32 v0, v2
	v_mul_f32_e32 v0, v4, v3
	v_add_u32_e32 v1, 0x1ff7c, v156
	ds_write_b32 v1, v0
.Ltp3_L1_f_a1:
	s_or_b64 exec, exec, s[6:7]
	s_mov_b64 s[6:7], exec
	s_andn2_b64 exec, exec, s[0:1]
	s_cbranch_execz .Ltp3_L1_f_b1
	s_nop 9
	v_add_u32_e32 v4, 32, v155
	v_cvt_f32_i32_e32 v4, v4
	v_mul_f32_e32 v4, 0xb9000400, v4
	v_mul_f32_e64 v5, |v144|, v4
	v_mul_f32_e64 v4, |v147|, v4
	v_mul_f32_e32 v5, 0x3fb8aa3b, v5
	v_mul_f32_e32 v4, 0x3fb8aa3b, v4
	v_exp_f32_e32 v5, v5
	v_exp_f32_e32 v4, v4
	v_mul_f32_e32 v0, v5, v0
	v_mul_f32_e32 v1, v4, v1
	v_mul_f32_e32 v2, v5, v2
	global_store_dword v189, v0, s[86:87] offset:128
	global_store_dword v191, v1, s[86:87] offset:3964
	v_add_u32_e32 v0, 0x10080, v189
	global_store_dword v0, v2, s[86:87]
	v_mul_f32_e32 v0, v4, v3
	v_add_u32_e32 v1, 0x1ff7c, v190
	global_store_dword v1, v0, s[86:87]
.Ltp3_L1_f_b1:
	s_mov_b64 exec, s[6:7]
	s_waitcnt vmcnt(39)
	v_mfma_f32_32x32x16_bf16 v[0:15], v[16:19], v[124:127], 0
	s_waitcnt vmcnt(38)
	v_mfma_f32_32x32x16_bf16 v[0:15], v[20:23], v[120:123], v[0:15]
	s_waitcnt vmcnt(37)
	v_mfma_f32_32x32x16_bf16 v[0:15], v[24:27], v[116:119], v[0:15]
	s_waitcnt vmcnt(36)
	v_mfma_f32_32x32x16_bf16 v[0:15], v[28:31], v[112:115], v[0:15]
	global_load_dwordx4 v[124:127], v182, s[98:99]
	global_load_dwordx4 v[120:123], v182, s[98:99] offset:1024
	global_load_dwordx4 v[116:119], v182, s[98:99] offset:2048
	global_load_dwordx4 v[112:115], v182, s[98:99] offset:3072
	s_and_saveexec_b64 s[6:7], s[0:1]
	s_cbranch_execz .Ltp3_L1_f_a2
	s_nop 9
	v_add_u32_e32 v4, 64, v155
	v_cvt_f32_i32_e32 v4, v4
	v_mul_f32_e32 v4, 0xb9000400, v4
	v_mul_f32_e64 v5, |v144|, v4
	v_mul_f32_e64 v4, |v147|, v4
	v_mul_f32_e32 v5, 0x3fb8aa3b, v5
	v_mul_f32_e32 v4, 0x3fb8aa3b, v4
	v_exp_f32_e32 v5, v5
	v_exp_f32_e32 v4, v4
	v_mul_f32_e32 v0, v5, v0
	v_mul_f32_e32 v1, v4, v1
	v_mul_f32_e32 v2, v5, v2
	ds_write_b32 v157, v0 offset:256
	ds_write_b32 v156, v1 offset:65276
	v_add_u32_e32 v0, 0x10100, v157
	ds_write_b32 v0, v2
	v_mul_f32_e32 v0, v4, v3
	v_add_u32_e32 v1, 0x1fefc, v156
	ds_write_b32 v1, v0
.Ltp3_L1_f_a2:
	s_or_b64 exec, exec, s[6:7]
	s_mov_b64 s[6:7], exec
	s_andn2_b64 exec, exec, s[0:1]
	s_cbranch_execz .Ltp3_L1_f_b2
	s_nop 9
	v_add_u32_e32 v4, 64, v155
	v_cvt_f32_i32_e32 v4, v4
	v_mul_f32_e32 v4, 0xb9000400, v4
	v_mul_f32_e64 v5, |v144|, v4
	v_mul_f32_e64 v4, |v147|, v4
	v_mul_f32_e32 v5, 0x3fb8aa3b, v5
	v_mul_f32_e32 v4, 0x3fb8aa3b, v4
	v_exp_f32_e32 v5, v5
	v_exp_f32_e32 v4, v4
	v_mul_f32_e32 v0, v5, v0
	v_mul_f32_e32 v1, v4, v1
	v_mul_f32_e32 v2, v5, v2
	global_store_dword v189, v0, s[86:87] offset:256
	global_store_dword v191, v1, s[86:87] offset:3836
	v_add_u32_e32 v0, 0x10100, v189
	global_store_dword v0, v2, s[86:87]
	v_mul_f32_e32 v0, v4, v3
	v_add_u32_e32 v1, 0x1fefc, v190
	global_store_dword v1, v0, s[86:87]
.Ltp3_L1_f_b2:
	s_mov_b64 exec, s[6:7]
	s_waitcnt vmcnt(43)
	v_mfma_f32_32x32x16_bf16 v[0:15], v[16:19], v[108:111], 0
	s_waitcnt vmcnt(42)
	v_mfma_f32_32x32x16_bf16 v[0:15], v[20:23], v[104:107], v[0:15]
	s_waitcnt vmcnt(41)
	v_mfma_f32_32x32x16_bf16 v[0:15], v[24:27], v[100:103], v[0:15]
	s_waitcnt vmcnt(40)
	v_mfma_f32_32x32x16_bf16 v[0:15], v[28:31], v[96:99], v[0:15]
	global_load_dwordx4 v[108:111], v183, s[98:99]
	global_load_dwordx4 v[104:107], v183, s[98:99] offset:1024
	global_load_dwordx4 v[100:103], v183, s[98:99] offset:2048
	global_load_dwordx4 v[96:99], v183, s[98:99] offset:3072
	s_and_saveexec_b64 s[6:7], s[0:1]
	s_cbranch_execz .Ltp3_L1_f_a3
	s_nop 9
	v_add_u32_e32 v4, 0x60, v155
	v_cvt_f32_i32_e32 v4, v4
	v_mul_f32_e32 v4, 0xb9000400, v4
	v_mul_f32_e64 v5, |v144|, v4
	v_mul_f32_e64 v4, |v147|, v4
	v_mul_f32_e32 v5, 0x3fb8aa3b, v5
	v_mul_f32_e32 v4, 0x3fb8aa3b, v4
	v_exp_f32_e32 v5, v5
	v_exp_f32_e32 v4, v4
	v_mul_f32_e32 v0, v5, v0
	v_mul_f32_e32 v1, v4, v1
	v_mul_f32_e32 v2, v5, v2
	ds_write_b32 v157, v0 offset:384
	ds_write_b32 v156, v1 offset:65148
	v_add_u32_e32 v0, 0x10180, v157
	ds_write_b32 v0, v2
	v_mul_f32_e32 v0, v4, v3
	v_add_u32_e32 v1, 0x1fe7c, v156
	ds_write_b32 v1, v0
.Ltp3_L1_f_a3:
	s_or_b64 exec, exec, s[6:7]
	s_mov_b64 s[6:7], exec
	s_andn2_b64 exec, exec, s[0:1]
	s_cbranch_execz .Ltp3_L1_f_b3
	s_nop 9
	v_add_u32_e32 v4, 0x60, v155
	v_cvt_f32_i32_e32 v4, v4
	v_mul_f32_e32 v4, 0xb9000400, v4
	v_mul_f32_e64 v5, |v144|, v4
	v_mul_f32_e64 v4, |v147|, v4
	v_mul_f32_e32 v5, 0x3fb8aa3b, v5
	v_mul_f32_e32 v4, 0x3fb8aa3b, v4
	v_exp_f32_e32 v5, v5
	v_exp_f32_e32 v4, v4
	v_mul_f32_e32 v0, v5, v0
	v_mul_f32_e32 v1, v4, v1
	v_mul_f32_e32 v2, v5, v2
	global_store_dword v189, v0, s[86:87] offset:384
	global_store_dword v191, v1, s[86:87] offset:3708
	v_add_u32_e32 v0, 0x10180, v189
	global_store_dword v0, v2, s[86:87]
	v_mul_f32_e32 v0, v4, v3
	v_add_u32_e32 v1, 0x1fe7c, v190
	global_store_dword v1, v0, s[86:87]
.Ltp3_L1_f_b3:
	s_mov_b64 exec, s[6:7]
	s_waitcnt vmcnt(47)
	v_mfma_f32_32x32x16_bf16 v[0:15], v[16:19], v[92:95], 0
	s_waitcnt vmcnt(46)
	v_mfma_f32_32x32x16_bf16 v[0:15], v[20:23], v[88:91], v[0:15]
	s_waitcnt vmcnt(45)
	v_mfma_f32_32x32x16_bf16 v[0:15], v[24:27], v[84:87], v[0:15]
	s_waitcnt vmcnt(44)
	v_mfma_f32_32x32x16_bf16 v[0:15], v[28:31], v[80:83], v[0:15]
	global_load_dwordx4 v[92:95], v184, s[98:99]
	global_load_dwordx4 v[88:91], v184, s[98:99] offset:1024
	global_load_dwordx4 v[84:87], v184, s[98:99] offset:2048
	global_load_dwordx4 v[80:83], v184, s[98:99] offset:3072
	s_and_saveexec_b64 s[6:7], s[0:1]
	s_cbranch_execz .Ltp3_L1_f_a4
	s_nop 9
	v_add_u32_e32 v4, 0x80, v155
	v_cvt_f32_i32_e32 v4, v4
	v_mul_f32_e32 v4, 0xb9000400, v4
	v_mul_f32_e64 v5, |v144|, v4
	v_mul_f32_e64 v4, |v147|, v4
	v_mul_f32_e32 v5, 0x3fb8aa3b, v5
	v_mul_f32_e32 v4, 0x3fb8aa3b, v4
	v_exp_f32_e32 v5, v5
	v_exp_f32_e32 v4, v4
	v_mul_f32_e32 v0, v5, v0
	v_mul_f32_e32 v1, v4, v1
	v_mul_f32_e32 v2, v5, v2
	ds_write_b32 v157, v0 offset:512
	ds_write_b32 v156, v1 offset:65020
	v_add_u32_e32 v0, 0x10200, v157
	ds_write_b32 v0, v2
	v_mul_f32_e32 v0, v4, v3
	v_add_u32_e32 v1, 0x1fdfc, v156
	ds_write_b32 v1, v0
.Ltp3_L1_f_a4:
	s_or_b64 exec, exec, s[6:7]
	s_mov_b64 s[6:7], exec
	s_andn2_b64 exec, exec, s[0:1]
	s_cbranch_execz .Ltp3_L1_f_b4
	s_nop 9
	v_add_u32_e32 v4, 0x80, v155
	v_cvt_f32_i32_e32 v4, v4
	v_mul_f32_e32 v4, 0xb9000400, v4
	v_mul_f32_e64 v5, |v144|, v4
	v_mul_f32_e64 v4, |v147|, v4
	v_mul_f32_e32 v5, 0x3fb8aa3b, v5
	v_mul_f32_e32 v4, 0x3fb8aa3b, v4
	v_exp_f32_e32 v5, v5
	v_exp_f32_e32 v4, v4
	v_mul_f32_e32 v0, v5, v0
	v_mul_f32_e32 v1, v4, v1
	v_mul_f32_e32 v2, v5, v2
	global_store_dword v189, v0, s[86:87] offset:512
	global_store_dword v191, v1, s[86:87] offset:3580
	v_add_u32_e32 v0, 0x10200, v189
	global_store_dword v0, v2, s[86:87]
	v_mul_f32_e32 v0, v4, v3
	v_add_u32_e32 v1, 0x1fdfc, v190
	global_store_dword v1, v0, s[86:87]
.Ltp3_L1_f_b4:
	s_mov_b64 exec, s[6:7]
	s_waitcnt vmcnt(51)
	v_mfma_f32_32x32x16_bf16 v[0:15], v[16:19], v[76:79], 0
	s_waitcnt vmcnt(50)
	v_mfma_f32_32x32x16_bf16 v[0:15], v[20:23], v[68:71], v[0:15]
	s_waitcnt vmcnt(49)
	v_mfma_f32_32x32x16_bf16 v[0:15], v[24:27], v[56:59], v[0:15]
	s_waitcnt vmcnt(48)
	v_mfma_f32_32x32x16_bf16 v[0:15], v[28:31], v[48:51], v[0:15]
	global_load_dwordx4 v[76:79], v185, s[98:99]
	global_load_dwordx4 v[68:71], v185, s[98:99] offset:1024
	global_load_dwordx4 v[56:59], v185, s[98:99] offset:2048
	global_load_dwordx4 v[48:51], v185, s[98:99] offset:3072
	s_and_saveexec_b64 s[6:7], s[0:1]
	s_cbranch_execz .Ltp3_L1_f_a5
	s_nop 9
	v_add_u32_e32 v4, 0xa0, v155
	v_cvt_f32_i32_e32 v4, v4
	v_mul_f32_e32 v4, 0xb9000400, v4
	v_mul_f32_e64 v5, |v144|, v4
	v_mul_f32_e64 v4, |v147|, v4
	v_mul_f32_e32 v5, 0x3fb8aa3b, v5
	v_mul_f32_e32 v4, 0x3fb8aa3b, v4
	v_exp_f32_e32 v5, v5
	v_exp_f32_e32 v4, v4
	v_mul_f32_e32 v0, v5, v0
	v_mul_f32_e32 v1, v4, v1
	v_mul_f32_e32 v2, v5, v2
	ds_write_b32 v157, v0 offset:640
	ds_write_b32 v156, v1 offset:64892
	v_add_u32_e32 v0, 0x10280, v157
	ds_write_b32 v0, v2
	v_mul_f32_e32 v0, v4, v3
	v_add_u32_e32 v1, 0x1fd7c, v156
	ds_write_b32 v1, v0
.Ltp3_L1_f_a5:
	s_or_b64 exec, exec, s[6:7]
	s_mov_b64 s[6:7], exec
	s_andn2_b64 exec, exec, s[0:1]
	s_cbranch_execz .Ltp3_L1_f_b5
	s_nop 9
	v_add_u32_e32 v4, 0xa0, v155
	v_cvt_f32_i32_e32 v4, v4
	v_mul_f32_e32 v4, 0xb9000400, v4
	v_mul_f32_e64 v5, |v144|, v4
	v_mul_f32_e64 v4, |v147|, v4
	v_mul_f32_e32 v5, 0x3fb8aa3b, v5
	v_mul_f32_e32 v4, 0x3fb8aa3b, v4
	v_exp_f32_e32 v5, v5
	v_exp_f32_e32 v4, v4
	v_mul_f32_e32 v0, v5, v0
	v_mul_f32_e32 v1, v4, v1
	v_mul_f32_e32 v2, v5, v2
	global_store_dword v189, v0, s[86:87] offset:640
	global_store_dword v191, v1, s[86:87] offset:3452
	v_add_u32_e32 v0, 0x10280, v189
	global_store_dword v0, v2, s[86:87]
	v_mul_f32_e32 v0, v4, v3
	v_add_u32_e32 v1, 0x1fd7c, v190
	global_store_dword v1, v0, s[86:87]
.Ltp3_L1_f_b5:
	s_mov_b64 exec, s[6:7]
	s_waitcnt vmcnt(55)
	v_mfma_f32_32x32x16_bf16 v[0:15], v[16:19], v[72:75], 0
	s_waitcnt vmcnt(54)
	v_mfma_f32_32x32x16_bf16 v[0:15], v[20:23], v[60:63], v[0:15]
	s_waitcnt vmcnt(53)
	v_mfma_f32_32x32x16_bf16 v[0:15], v[24:27], v[64:67], v[0:15]
	s_waitcnt vmcnt(52)
	v_mfma_f32_32x32x16_bf16 v[0:15], v[28:31], v[52:55], v[0:15]
	global_load_dwordx4 v[72:75], v186, s[98:99]
	global_load_dwordx4 v[60:63], v186, s[98:99] offset:1024
	global_load_dwordx4 v[64:67], v186, s[98:99] offset:2048
	global_load_dwordx4 v[52:55], v186, s[98:99] offset:3072
	s_and_saveexec_b64 s[6:7], s[0:1]
	s_cbranch_execz .Ltp3_L1_f_a6
	s_nop 9
	v_add_u32_e32 v4, 0xc0, v155
	v_cvt_f32_i32_e32 v4, v4
	v_mul_f32_e32 v4, 0xb9000400, v4
	v_mul_f32_e64 v5, |v144|, v4
	v_mul_f32_e64 v4, |v147|, v4
	v_mul_f32_e32 v5, 0x3fb8aa3b, v5
	v_mul_f32_e32 v4, 0x3fb8aa3b, v4
	v_exp_f32_e32 v5, v5
	v_exp_f32_e32 v4, v4
	v_mul_f32_e32 v0, v5, v0
	v_mul_f32_e32 v1, v4, v1
	v_mul_f32_e32 v2, v5, v2
	ds_write_b32 v157, v0 offset:768
	ds_write_b32 v156, v1 offset:64764
	v_add_u32_e32 v0, 0x10300, v157
	ds_write_b32 v0, v2
	v_mul_f32_e32 v0, v4, v3
	v_add_u32_e32 v1, 0x1fcfc, v156
	ds_write_b32 v1, v0
.Ltp3_L1_f_a6:
	s_or_b64 exec, exec, s[6:7]
	s_mov_b64 s[6:7], exec
	s_andn2_b64 exec, exec, s[0:1]
	s_cbranch_execz .Ltp3_L1_f_b6
	s_nop 9
	v_add_u32_e32 v4, 0xc0, v155
	v_cvt_f32_i32_e32 v4, v4
	v_mul_f32_e32 v4, 0xb9000400, v4
	v_mul_f32_e64 v5, |v144|, v4
	v_mul_f32_e64 v4, |v147|, v4
	v_mul_f32_e32 v5, 0x3fb8aa3b, v5
	v_mul_f32_e32 v4, 0x3fb8aa3b, v4
	v_exp_f32_e32 v5, v5
	v_exp_f32_e32 v4, v4
	v_mul_f32_e32 v0, v5, v0
	v_mul_f32_e32 v1, v4, v1
	v_mul_f32_e32 v2, v5, v2
	global_store_dword v189, v0, s[86:87] offset:768
	global_store_dword v191, v1, s[86:87] offset:3324
	v_add_u32_e32 v0, 0x10300, v189
	global_store_dword v0, v2, s[86:87]
	v_mul_f32_e32 v0, v4, v3
	v_add_u32_e32 v1, 0x1fcfc, v190
	global_store_dword v1, v0, s[86:87]
.Ltp3_L1_f_b6:
	s_mov_b64 exec, s[6:7]
	s_waitcnt vmcnt(59)
	v_mfma_f32_32x32x16_bf16 v[0:15], v[16:19], v[36:39], 0
	s_waitcnt vmcnt(58)
	v_mfma_f32_32x32x16_bf16 v[0:15], v[20:23], v[32:35], v[0:15]
	s_waitcnt vmcnt(57)
	v_mfma_f32_32x32x16_bf16 v[0:15], v[24:27], v[40:43], v[0:15]
	s_waitcnt vmcnt(56)
	v_mfma_f32_32x32x16_bf16 v[0:15], v[28:31], v[44:47], v[0:15]
	global_load_dwordx4 v[36:39], v187, s[98:99]
	global_load_dwordx4 v[32:35], v187, s[98:99] offset:1024
	global_load_dwordx4 v[40:43], v187, s[98:99] offset:2048
	global_load_dwordx4 v[44:47], v187, s[98:99] offset:3072
	s_and_saveexec_b64 s[6:7], s[0:1]
	s_cbranch_execz .Ltp3_L1_f_a7
	s_nop 9
	v_add_u32_e32 v4, 0xe0, v155
	v_cvt_f32_i32_e32 v4, v4
	s_movk_i32 s8, 0x1f1f
	v_cmp_ne_u32_e32 vcc, s8, v155
	v_mul_f32_e32 v4, 0xb9000400, v4
	v_mul_f32_e64 v5, |v144|, v4
	v_mul_f32_e64 v4, |v147|, v4
	v_mul_f32_e32 v5, 0x3fb8aa3b, v5
	v_mul_f32_e32 v4, 0x3fb8aa3b, v4
	v_exp_f32_e32 v4, v4
	v_exp_f32_e32 v5, v5
	v_cndmask_b32_e32 v4, 0, v4, vcc
	v_mul_f32_e32 v0, v5, v0
	ds_write_b32 v157, v0 offset:896
	v_mul_f32_e32 v0, v4, v1
	ds_write_b32 v156, v0 offset:64636
	v_mul_f32_e32 v0, v5, v2
	v_add_u32_e32 v1, 0x10380, v157
	ds_write_b32 v1, v0
	v_mul_f32_e32 v0, v4, v3
	v_add_u32_e32 v1, 0x1fc7c, v156
	ds_write_b32 v1, v0
.Ltp3_L1_f_a7:
	s_or_b64 exec, exec, s[6:7]
	s_mov_b64 s[6:7], exec
	s_andn2_b64 exec, exec, s[0:1]
	s_cbranch_execz .Ltp3_L1_f_b7
	s_nop 9
	v_add_u32_e32 v4, 0xe0, v155
	v_cvt_f32_i32_e32 v4, v4
	s_movk_i32 s8, 0x1f1f
	v_cmp_ne_u32_e32 vcc, s8, v155
	v_mul_f32_e32 v4, 0xb9000400, v4
	v_mul_f32_e64 v5, |v144|, v4
	v_mul_f32_e64 v4, |v147|, v4
	v_mul_f32_e32 v5, 0x3fb8aa3b, v5
	v_mul_f32_e32 v4, 0x3fb8aa3b, v4
	v_exp_f32_e32 v4, v4
	v_exp_f32_e32 v5, v5
	v_cndmask_b32_e32 v4, 0, v4, vcc
	v_mul_f32_e32 v0, v5, v0
	global_store_dword v189, v0, s[86:87] offset:896
	v_mul_f32_e32 v0, v4, v1
	global_store_dword v191, v0, s[86:87] offset:3196
	v_mul_f32_e32 v0, v5, v2
	v_add_u32_e32 v1, 0x10380, v189
	global_store_dword v1, v0, s[86:87]
	v_mul_f32_e32 v0, v4, v3
	v_add_u32_e32 v1, 0x1fc7c, v190
	global_store_dword v1, v0, s[86:87]
.Ltp3_L1_f_b7:
	s_mov_b64 exec, s[6:7]
	v_add_u32_e32 v153, 0x400, v153
	v_add_u32_e32 v154, 0xfffffc00, v154
	v_add_u32_e32 v155, 0x100, v155
	s_mov_b32 s4, 0
.Ltp3_loop_L1:
	s_add_u32 s98, s98, 0x8000
	s_addc_u32 s99, s99, 0
	v_add_u32_e32 v157, 16, v153
	v_add_u32_e32 v156, 16, v154
	v_add_u32_e32 v189, v188, v153
	v_add_u32_e32 v190, v188, v154
	v_add_u32_e32 v191, 0xf000, v190
	s_waitcnt vmcnt(63)
	v_mfma_f32_32x32x16_bf16 v[0:15], v[16:19], v[164:167], 0
	s_waitcnt vmcnt(62)
	v_mfma_f32_32x32x16_bf16 v[0:15], v[20:23], v[168:171], v[0:15]
	s_waitcnt vmcnt(61)
	v_mfma_f32_32x32x16_bf16 v[0:15], v[24:27], v[172:175], v[0:15]
	s_waitcnt vmcnt(60)
	v_mfma_f32_32x32x16_bf16 v[0:15], v[28:31], v[176:179], v[0:15]
	global_load_dwordx4 v[164:167], v180, s[98:99]
	global_load_dwordx4 v[168:171], v180, s[98:99] offset:1024
	global_load_dwordx4 v[172:175], v180, s[98:99] offset:2048
	global_load_dwordx4 v[176:179], v180, s[98:99] offset:3072
	s_and_saveexec_b64 s[6:7], s[0:1]
	s_cbranch_execz .Ltp3_L1_m_a0
	s_nop 7
	v_cvt_f32_i32_e32 v4, v155
	v_mul_f32_e32 v4, 0xb9000400, v4
	v_mul_f32_e64 v5, |v144|, v4
	v_mul_f32_e64 v4, |v147|, v4
	v_mul_f32_e32 v5, 0x3fb8aa3b, v5
	v_mul_f32_e32 v4, 0x3fb8aa3b, v4
	v_exp_f32_e32 v5, v5
	v_exp_f32_e32 v4, v4
	v_mul_f32_e32 v0, v5, v0
	v_mul_f32_e32 v1, v4, v1
	v_mul_f32_e32 v2, v5, v2
	ds_write_b32 v157, v0
	ds_write_b32 v156, v1 offset:65532
	v_add_u32_e32 v0, 0x10000, v157
	ds_write_b32 v0, v2
	v_mul_f32_e32 v0, v4, v3
	v_add_u32_e32 v1, 0x1fffc, v156
	ds_write_b32 v1, v0

.Ltp3_L1_m_b0:
	s_mov_b64 exec, s[6:7]
	s_waitcnt vmcnt(63)
	v_mfma_f32_32x32x16_bf16 v[0:15], v[16:19], v[140:143], 0
	s_waitcnt vmcnt(62)
	v_mfma_f32_32x32x16_bf16 v[0:15], v[20:23], v[136:139], v[0:15]
	s_waitcnt vmcnt(61)
	v_mfma_f32_32x32x16_bf16 v[0:15], v[24:27], v[132:135], v[0:15]
	s_waitcnt vmcnt(60)
	v_mfma_f32_32x32x16_bf16 v[0:15], v[28:31], v[128:131], v[0:15]
	global_load_dwordx4 v[140:143], v181, s[98:99]
	global_load_dwordx4 v[136:139], v181, s[98:99] offset:1024
	global_load_dwordx4 v[132:135], v181, s[98:99] offset:2048
	global_load_dwordx4 v[128:131], v181, s[98:99] offset:3072
	s_and_saveexec_b64 s[6:7], s[0:1]
	s_cbranch_execz .Ltp3_L1_m_a1
	s_nop 9
	v_add_u32_e32 v4, 32, v155
	v_cvt_f32_i32_e32 v4, v4
	v_mul_f32_e32 v4, 0xb9000400, v4
	v_mul_f32_e64 v5, |v144|, v4
	v_mul_f32_e64 v4, |v147|, v4
	v_mul_f32_e32 v5, 0x3fb8aa3b, v5
	v_mul_f32_e32 v4, 0x3fb8aa3b, v4
	v_exp_f32_e32 v5, v5
	v_exp_f32_e32 v4, v4
	v_mul_f32_e32 v0, v5, v0
	v_mul_f32_e32 v1, v4, v1
	v_mul_f32_e32 v2, v5, v2
	ds_write_b32 v157, v0 offset:128
	ds_write_b32 v156, v1 offset:65404
	v_add_u32_e32 v0, 0x10080, v157
	ds_write_b32 v0, v2
	v_mul_f32_e32 v0, v4, v3
	v_add_u32_e32 v1, 0x1ff7c, v156
	ds_write_b32 v1, v0

.Ltp3_L1_m_b1:
	s_mov_b64 exec, s[6:7]
	s_waitcnt vmcnt(63)
	v_mfma_f32_32x32x16_bf16 v[0:15], v[16:19], v[124:127], 0
	s_waitcnt vmcnt(62)
	v_mfma_f32_32x32x16_bf16 v[0:15], v[20:23], v[120:123], v[0:15]
	s_waitcnt vmcnt(61)
	v_mfma_f32_32x32x16_bf16 v[0:15], v[24:27], v[116:119], v[0:15]
	s_waitcnt vmcnt(60)
	v_mfma_f32_32x32x16_bf16 v[0:15], v[28:31], v[112:115], v[0:15]
	global_load_dwordx4 v[124:127], v182, s[98:99]
	global_load_dwordx4 v[120:123], v182, s[98:99] offset:1024
	global_load_dwordx4 v[116:119], v182, s[98:99] offset:2048
	global_load_dwordx4 v[112:115], v182, s[98:99] offset:3072
	s_and_saveexec_b64 s[6:7], s[0:1]
	s_cbranch_execz .Ltp3_L1_m_a2
	s_nop 9
	v_add_u32_e32 v4, 64, v155
	v_cvt_f32_i32_e32 v4, v4
	v_mul_f32_e32 v4, 0xb9000400, v4
	v_mul_f32_e64 v5, |v144|, v4
	v_mul_f32_e64 v4, |v147|, v4
	v_mul_f32_e32 v5, 0x3fb8aa3b, v5
	v_mul_f32_e32 v4, 0x3fb8aa3b, v4
	v_exp_f32_e32 v5, v5
	v_exp_f32_e32 v4, v4
	v_mul_f32_e32 v0, v5, v0
	v_mul_f32_e32 v1, v4, v1
	v_mul_f32_e32 v2, v5, v2
	ds_write_b32 v157, v0 offset:256
	ds_write_b32 v156, v1 offset:65276
	v_add_u32_e32 v0, 0x10100, v157
	ds_write_b32 v0, v2
	v_mul_f32_e32 v0, v4, v3
	v_add_u32_e32 v1, 0x1fefc, v156
	ds_write_b32 v1, v0

.Ltp3_L1_m_b2:
	s_mov_b64 exec, s[6:7]
	s_waitcnt vmcnt(63)
	v_mfma_f32_32x32x16_bf16 v[0:15], v[16:19], v[108:111], 0
	s_waitcnt vmcnt(62)
	v_mfma_f32_32x32x16_bf16 v[0:15], v[20:23], v[104:107], v[0:15]
	s_waitcnt vmcnt(61)
	v_mfma_f32_32x32x16_bf16 v[0:15], v[24:27], v[100:103], v[0:15]
	s_waitcnt vmcnt(60)
	v_mfma_f32_32x32x16_bf16 v[0:15], v[28:31], v[96:99], v[0:15]
	global_load_dwordx4 v[108:111], v183, s[98:99]
	global_load_dwordx4 v[104:107], v183, s[98:99] offset:1024
	global_load_dwordx4 v[100:103], v183, s[98:99] offset:2048
	global_load_dwordx4 v[96:99], v183, s[98:99] offset:3072
	s_and_saveexec_b64 s[6:7], s[0:1]
	s_cbranch_execz .Ltp3_L1_m_a3
	s_nop 9
	v_add_u32_e32 v4, 0x60, v155
	v_cvt_f32_i32_e32 v4, v4
	v_mul_f32_e32 v4, 0xb9000400, v4
	v_mul_f32_e64 v5, |v144|, v4
	v_mul_f32_e64 v4, |v147|, v4
	v_mul_f32_e32 v5, 0x3fb8aa3b, v5
	v_mul_f32_e32 v4, 0x3fb8aa3b, v4
	v_exp_f32_e32 v5, v5
	v_exp_f32_e32 v4, v4
	v_mul_f32_e32 v0, v5, v0
	v_mul_f32_e32 v1, v4, v1
	v_mul_f32_e32 v2, v5, v2
	ds_write_b32 v157, v0 offset:384
	ds_write_b32 v156, v1 offset:65148
	v_add_u32_e32 v0, 0x10180, v157
	ds_write_b32 v0, v2
	v_mul_f32_e32 v0, v4, v3
	v_add_u32_e32 v1, 0x1fe7c, v156
	ds_write_b32 v1, v0

.Ltp3_L1_m_b3:
	s_mov_b64 exec, s[6:7]
	s_waitcnt vmcnt(63)
	v_mfma_f32_32x32x16_bf16 v[0:15], v[16:19], v[92:95], 0
	s_waitcnt vmcnt(62)
	v_mfma_f32_32x32x16_bf16 v[0:15], v[20:23], v[88:91], v[0:15]
	s_waitcnt vmcnt(61)
	v_mfma_f32_32x32x16_bf16 v[0:15], v[24:27], v[84:87], v[0:15]
	s_waitcnt vmcnt(60)
	v_mfma_f32_32x32x16_bf16 v[0:15], v[28:31], v[80:83], v[0:15]
	global_load_dwordx4 v[92:95], v184, s[98:99]
	global_load_dwordx4 v[88:91], v184, s[98:99] offset:1024
	global_load_dwordx4 v[84:87], v184, s[98:99] offset:2048
	global_load_dwordx4 v[80:83], v184, s[98:99] offset:3072
	s_and_saveexec_b64 s[6:7], s[0:1]
	s_cbranch_execz .Ltp3_L1_m_a4
	s_nop 9
	v_add_u32_e32 v4, 0x80, v155
	v_cvt_f32_i32_e32 v4, v4
	v_mul_f32_e32 v4, 0xb9000400, v4
	v_mul_f32_e64 v5, |v144|, v4
	v_mul_f32_e64 v4, |v147|, v4
	v_mul_f32_e32 v5, 0x3fb8aa3b, v5
	v_mul_f32_e32 v4, 0x3fb8aa3b, v4
	v_exp_f32_e32 v5, v5
	v_exp_f32_e32 v4, v4
	v_mul_f32_e32 v0, v5, v0
	v_mul_f32_e32 v1, v4, v1
	v_mul_f32_e32 v2, v5, v2
	ds_write_b32 v157, v0 offset:512
	ds_write_b32 v156, v1 offset:65020
	v_add_u32_e32 v0, 0x10200, v157
	ds_write_b32 v0, v2
	v_mul_f32_e32 v0, v4, v3
	v_add_u32_e32 v1, 0x1fdfc, v156
	ds_write_b32 v1, v0

.Ltp3_L1_m_b4:
	s_mov_b64 exec, s[6:7]
	s_waitcnt vmcnt(63)
	v_mfma_f32_32x32x16_bf16 v[0:15], v[16:19], v[76:79], 0
	s_waitcnt vmcnt(62)
	v_mfma_f32_32x32x16_bf16 v[0:15], v[20:23], v[68:71], v[0:15]
	s_waitcnt vmcnt(61)
	v_mfma_f32_32x32x16_bf16 v[0:15], v[24:27], v[56:59], v[0:15]
	s_waitcnt vmcnt(60)
	v_mfma_f32_32x32x16_bf16 v[0:15], v[28:31], v[48:51], v[0:15]
	global_load_dwordx4 v[76:79], v185, s[98:99]
	global_load_dwordx4 v[68:71], v185, s[98:99] offset:1024
	global_load_dwordx4 v[56:59], v185, s[98:99] offset:2048
	global_load_dwordx4 v[48:51], v185, s[98:99] offset:3072
	s_and_saveexec_b64 s[6:7], s[0:1]
	s_cbranch_execz .Ltp3_L1_m_a5
	s_nop 9
	v_add_u32_e32 v4, 0xa0, v155
	v_cvt_f32_i32_e32 v4, v4
	v_mul_f32_e32 v4, 0xb9000400, v4
	v_mul_f32_e64 v5, |v144|, v4
	v_mul_f32_e64 v4, |v147|, v4
	v_mul_f32_e32 v5, 0x3fb8aa3b, v5
	v_mul_f32_e32 v4, 0x3fb8aa3b, v4
	v_exp_f32_e32 v5, v5
	v_exp_f32_e32 v4, v4
	v_mul_f32_e32 v0, v5, v0
	v_mul_f32_e32 v1, v4, v1
	v_mul_f32_e32 v2, v5, v2
	ds_write_b32 v157, v0 offset:640
	ds_write_b32 v156, v1 offset:64892
	v_add_u32_e32 v0, 0x10280, v157
	ds_write_b32 v0, v2
	v_mul_f32_e32 v0, v4, v3
	v_add_u32_e32 v1, 0x1fd7c, v156
	ds_write_b32 v1, v0

.Ltp3_L1_m_b5:
	s_mov_b64 exec, s[6:7]
	s_waitcnt vmcnt(63)
	v_mfma_f32_32x32x16_bf16 v[0:15], v[16:19], v[72:75], 0
	s_waitcnt vmcnt(62)
	v_mfma_f32_32x32x16_bf16 v[0:15], v[20:23], v[60:63], v[0:15]
	s_waitcnt vmcnt(61)
	v_mfma_f32_32x32x16_bf16 v[0:15], v[24:27], v[64:67], v[0:15]
	s_waitcnt vmcnt(60)
	v_mfma_f32_32x32x16_bf16 v[0:15], v[28:31], v[52:55], v[0:15]
	global_load_dwordx4 v[72:75], v186, s[98:99]
	global_load_dwordx4 v[60:63], v186, s[98:99] offset:1024
	global_load_dwordx4 v[64:67], v186, s[98:99] offset:2048
	global_load_dwordx4 v[52:55], v186, s[98:99] offset:3072
	s_and_saveexec_b64 s[6:7], s[0:1]
	s_cbranch_execz .Ltp3_L1_m_a6
	s_nop 9
	v_add_u32_e32 v4, 0xc0, v155
	v_cvt_f32_i32_e32 v4, v4
	v_mul_f32_e32 v4, 0xb9000400, v4
	v_mul_f32_e64 v5, |v144|, v4
	v_mul_f32_e64 v4, |v147|, v4
	v_mul_f32_e32 v5, 0x3fb8aa3b, v5
	v_mul_f32_e32 v4, 0x3fb8aa3b, v4
	v_exp_f32_e32 v5, v5
	v_exp_f32_e32 v4, v4
	v_mul_f32_e32 v0, v5, v0
	v_mul_f32_e32 v1, v4, v1
	v_mul_f32_e32 v2, v5, v2
	ds_write_b32 v157, v0 offset:768
	ds_write_b32 v156, v1 offset:64764
	v_add_u32_e32 v0, 0x10300, v157
	ds_write_b32 v0, v2
	v_mul_f32_e32 v0, v4, v3
	v_add_u32_e32 v1, 0x1fcfc, v156
	ds_write_b32 v1, v0

.Ltp3_L1_m_b6:
	s_mov_b64 exec, s[6:7]
	s_waitcnt vmcnt(63)
	v_mfma_f32_32x32x16_bf16 v[0:15], v[16:19], v[36:39], 0
	s_waitcnt vmcnt(62)
	v_mfma_f32_32x32x16_bf16 v[0:15], v[20:23], v[32:35], v[0:15]
	s_waitcnt vmcnt(61)
	v_mfma_f32_32x32x16_bf16 v[0:15], v[24:27], v[40:43], v[0:15]
	s_waitcnt vmcnt(60)
	v_mfma_f32_32x32x16_bf16 v[0:15], v[28:31], v[44:47], v[0:15]
	global_load_dwordx4 v[36:39], v187, s[98:99]
	global_load_dwordx4 v[32:35], v187, s[98:99] offset:1024
	global_load_dwordx4 v[40:43], v187, s[98:99] offset:2048
	global_load_dwordx4 v[44:47], v187, s[98:99] offset:3072
	s_and_saveexec_b64 s[6:7], s[0:1]
	s_cbranch_execz .Ltp3_L1_m_a7
	s_nop 9
	v_add_u32_e32 v4, 0xe0, v155
	v_cvt_f32_i32_e32 v4, v4
	s_movk_i32 s8, 0x1f1f
	v_cmp_ne_u32_e32 vcc, s8, v155
	v_mul_f32_e32 v4, 0xb9000400, v4
	v_mul_f32_e64 v5, |v144|, v4
	v_mul_f32_e64 v4, |v147|, v4
	v_mul_f32_e32 v5, 0x3fb8aa3b, v5
	v_mul_f32_e32 v4, 0x3fb8aa3b, v4
	v_exp_f32_e32 v4, v4
	v_exp_f32_e32 v5, v5
	v_cndmask_b32_e32 v4, 0, v4, vcc
	v_mul_f32_e32 v0, v5, v0
	ds_write_b32 v157, v0 offset:896
	v_mul_f32_e32 v0, v4, v1
	ds_write_b32 v156, v0 offset:64636
	v_mul_f32_e32 v0, v5, v2
	v_add_u32_e32 v1, 0x10380, v157
	ds_write_b32 v1, v0
	v_mul_f32_e32 v0, v4, v3
	v_add_u32_e32 v1, 0x1fc7c, v156
	ds_write_b32 v1, v0

.Ltp3_L1_m_b7:
	s_mov_b64 exec, s[6:7]
	v_add_u32_e32 v153, 0x400, v153
	v_add_u32_e32 v154, 0xfffffc00, v154
	v_add_u32_e32 v155, 0x100, v155
	s_add_i32 s4, s4, 1
	s_cmp_lt_u32 s4, 2
	s_cbranch_scc1 .Ltp3_loop_L1
	v_add_u32_e32 v157, 16, v153
	v_add_u32_e32 v156, 16, v154
	v_add_u32_e32 v189, v188, v153
	v_add_u32_e32 v190, v188, v154
	v_add_u32_e32 v191, 0xf000, v190
	s_waitcnt vmcnt(63)
	v_mfma_f32_32x32x16_bf16 v[0:15], v[16:19], v[164:167], 0
	s_waitcnt vmcnt(62)
	v_mfma_f32_32x32x16_bf16 v[0:15], v[20:23], v[168:171], v[0:15]
	s_waitcnt vmcnt(61)
	v_mfma_f32_32x32x16_bf16 v[0:15], v[24:27], v[172:175], v[0:15]
	s_waitcnt vmcnt(60)
	v_mfma_f32_32x32x16_bf16 v[0:15], v[28:31], v[176:179], v[0:15]
	s_and_saveexec_b64 s[6:7], s[0:1]
	s_cbranch_execz .Ltp3_L1_l_a0
	s_nop 7
	v_cvt_f32_i32_e32 v4, v155
	v_mul_f32_e32 v4, 0xb9000400, v4
	v_mul_f32_e64 v5, |v144|, v4
	v_mul_f32_e64 v4, |v147|, v4
	v_mul_f32_e32 v5, 0x3fb8aa3b, v5
	v_mul_f32_e32 v4, 0x3fb8aa3b, v4
	v_exp_f32_e32 v5, v5
	v_exp_f32_e32 v4, v4
	v_mul_f32_e32 v0, v5, v0
	v_mul_f32_e32 v1, v4, v1
	v_mul_f32_e32 v2, v5, v2
	ds_write_b32 v157, v0
	ds_write_b32 v156, v1 offset:65532
	v_add_u32_e32 v0, 0x10000, v157
	ds_write_b32 v0, v2
	v_mul_f32_e32 v0, v4, v3
	v_add_u32_e32 v1, 0x1fffc, v156
	ds_write_b32 v1, v0

.Ltp3_L1_l_b0:
	s_mov_b64 exec, s[6:7]
	s_waitcnt vmcnt(59)
	v_mfma_f32_32x32x16_bf16 v[0:15], v[16:19], v[140:143], 0
	s_waitcnt vmcnt(58)
	v_mfma_f32_32x32x16_bf16 v[0:15], v[20:23], v[136:139], v[0:15]
	s_waitcnt vmcnt(57)
	v_mfma_f32_32x32x16_bf16 v[0:15], v[24:27], v[132:135], v[0:15]
	s_waitcnt vmcnt(56)
	v_mfma_f32_32x32x16_bf16 v[0:15], v[28:31], v[128:131], v[0:15]
	s_and_saveexec_b64 s[6:7], s[0:1]
	s_cbranch_execz .Ltp3_L1_l_a1
	s_nop 9
	v_add_u32_e32 v4, 32, v155
	v_cvt_f32_i32_e32 v4, v4
	v_mul_f32_e32 v4, 0xb9000400, v4
	v_mul_f32_e64 v5, |v144|, v4
	v_mul_f32_e64 v4, |v147|, v4
	v_mul_f32_e32 v5, 0x3fb8aa3b, v5
	v_mul_f32_e32 v4, 0x3fb8aa3b, v4
	v_exp_f32_e32 v5, v5
	v_exp_f32_e32 v4, v4
	v_mul_f32_e32 v0, v5, v0
	v_mul_f32_e32 v1, v4, v1
	v_mul_f32_e32 v2, v5, v2
	ds_write_b32 v157, v0 offset:128
	ds_write_b32 v156, v1 offset:65404
	v_add_u32_e32 v0, 0x10080, v157
	ds_write_b32 v0, v2
	v_mul_f32_e32 v0, v4, v3
	v_add_u32_e32 v1, 0x1ff7c, v156
	ds_write_b32 v1, v0

.Ltp3_L1_l_b1:
	s_mov_b64 exec, s[6:7]
	s_waitcnt vmcnt(55)
	v_mfma_f32_32x32x16_bf16 v[0:15], v[16:19], v[124:127], 0
	s_waitcnt vmcnt(54)
	v_mfma_f32_32x32x16_bf16 v[0:15], v[20:23], v[120:123], v[0:15]
	s_waitcnt vmcnt(53)
	v_mfma_f32_32x32x16_bf16 v[0:15], v[24:27], v[116:119], v[0:15]
	s_waitcnt vmcnt(52)
	v_mfma_f32_32x32x16_bf16 v[0:15], v[28:31], v[112:115], v[0:15]
	s_and_saveexec_b64 s[6:7], s[0:1]
	s_cbranch_execz .Ltp3_L1_l_a2
	s_nop 9
	v_add_u32_e32 v4, 64, v155
	v_cvt_f32_i32_e32 v4, v4
	v_mul_f32_e32 v4, 0xb9000400, v4
	v_mul_f32_e64 v5, |v144|, v4
	v_mul_f32_e64 v4, |v147|, v4
	v_mul_f32_e32 v5, 0x3fb8aa3b, v5
	v_mul_f32_e32 v4, 0x3fb8aa3b, v4
	v_exp_f32_e32 v5, v5
	v_exp_f32_e32 v4, v4
	v_mul_f32_e32 v0, v5, v0
	v_mul_f32_e32 v1, v4, v1
	v_mul_f32_e32 v2, v5, v2
	ds_write_b32 v157, v0 offset:256
	ds_write_b32 v156, v1 offset:65276
	v_add_u32_e32 v0, 0x10100, v157
	ds_write_b32 v0, v2
	v_mul_f32_e32 v0, v4, v3
	v_add_u32_e32 v1, 0x1fefc, v156
	ds_write_b32 v1, v0

.Ltp3_L1_l_b2:
	s_mov_b64 exec, s[6:7]
	s_waitcnt vmcnt(51)
	v_mfma_f32_32x32x16_bf16 v[0:15], v[16:19], v[108:111], 0
	s_waitcnt vmcnt(50)
	v_mfma_f32_32x32x16_bf16 v[0:15], v[20:23], v[104:107], v[0:15]
	s_waitcnt vmcnt(49)
	v_mfma_f32_32x32x16_bf16 v[0:15], v[24:27], v[100:103], v[0:15]
	s_waitcnt vmcnt(48)
	v_mfma_f32_32x32x16_bf16 v[0:15], v[28:31], v[96:99], v[0:15]
	s_and_saveexec_b64 s[6:7], s[0:1]
	s_cbranch_execz .Ltp3_L1_l_a3
	s_nop 9
	v_add_u32_e32 v4, 0x60, v155
	v_cvt_f32_i32_e32 v4, v4
	v_mul_f32_e32 v4, 0xb9000400, v4
	v_mul_f32_e64 v5, |v144|, v4
	v_mul_f32_e64 v4, |v147|, v4
	v_mul_f32_e32 v5, 0x3fb8aa3b, v5
	v_mul_f32_e32 v4, 0x3fb8aa3b, v4
	v_exp_f32_e32 v5, v5
	v_exp_f32_e32 v4, v4
	v_mul_f32_e32 v0, v5, v0
	v_mul_f32_e32 v1, v4, v1
	v_mul_f32_e32 v2, v5, v2
	ds_write_b32 v157, v0 offset:384
	ds_write_b32 v156, v1 offset:65148
	v_add_u32_e32 v0, 0x10180, v157
	ds_write_b32 v0, v2
	v_mul_f32_e32 v0, v4, v3
	v_add_u32_e32 v1, 0x1fe7c, v156
	ds_write_b32 v1, v0

.Ltp3_L1_l_b3:
	s_mov_b64 exec, s[6:7]
	s_waitcnt vmcnt(47)
	v_mfma_f32_32x32x16_bf16 v[0:15], v[16:19], v[92:95], 0
	s_waitcnt vmcnt(46)
	v_mfma_f32_32x32x16_bf16 v[0:15], v[20:23], v[88:91], v[0:15]
	s_waitcnt vmcnt(45)
	v_mfma_f32_32x32x16_bf16 v[0:15], v[24:27], v[84:87], v[0:15]
	s_waitcnt vmcnt(44)
	v_mfma_f32_32x32x16_bf16 v[0:15], v[28:31], v[80:83], v[0:15]
	s_and_saveexec_b64 s[6:7], s[0:1]
	s_cbranch_execz .Ltp3_L1_l_a4
	s_nop 9
	v_add_u32_e32 v4, 0x80, v155
	v_cvt_f32_i32_e32 v4, v4
	v_mul_f32_e32 v4, 0xb9000400, v4
	v_mul_f32_e64 v5, |v144|, v4
	v_mul_f32_e64 v4, |v147|, v4
	v_mul_f32_e32 v5, 0x3fb8aa3b, v5
	v_mul_f32_e32 v4, 0x3fb8aa3b, v4
	v_exp_f32_e32 v5, v5
	v_exp_f32_e32 v4, v4
	v_mul_f32_e32 v0, v5, v0
	v_mul_f32_e32 v1, v4, v1
	v_mul_f32_e32 v2, v5, v2
	ds_write_b32 v157, v0 offset:512
	ds_write_b32 v156, v1 offset:65020
	v_add_u32_e32 v0, 0x10200, v157
	ds_write_b32 v0, v2
	v_mul_f32_e32 v0, v4, v3
	v_add_u32_e32 v1, 0x1fdfc, v156
	ds_write_b32 v1, v0

.Ltp3_L1_l_b4:
	s_mov_b64 exec, s[6:7]
	s_waitcnt vmcnt(43)
	v_mfma_f32_32x32x16_bf16 v[0:15], v[16:19], v[76:79], 0
	s_waitcnt vmcnt(42)
	v_mfma_f32_32x32x16_bf16 v[0:15], v[20:23], v[68:71], v[0:15]
	s_waitcnt vmcnt(41)
	v_mfma_f32_32x32x16_bf16 v[0:15], v[24:27], v[56:59], v[0:15]
	s_waitcnt vmcnt(40)
	v_mfma_f32_32x32x16_bf16 v[0:15], v[28:31], v[48:51], v[0:15]
	s_and_saveexec_b64 s[6:7], s[0:1]
	s_cbranch_execz .Ltp3_L1_l_a5
	s_nop 9
	v_add_u32_e32 v4, 0xa0, v155
	v_cvt_f32_i32_e32 v4, v4
	v_mul_f32_e32 v4, 0xb9000400, v4
	v_mul_f32_e64 v5, |v144|, v4
	v_mul_f32_e64 v4, |v147|, v4
	v_mul_f32_e32 v5, 0x3fb8aa3b, v5
	v_mul_f32_e32 v4, 0x3fb8aa3b, v4
	v_exp_f32_e32 v5, v5
	v_exp_f32_e32 v4, v4
	v_mul_f32_e32 v0, v5, v0
	v_mul_f32_e32 v1, v4, v1
	v_mul_f32_e32 v2, v5, v2
	ds_write_b32 v157, v0 offset:640
	ds_write_b32 v156, v1 offset:64892
	v_add_u32_e32 v0, 0x10280, v157
	ds_write_b32 v0, v2
	v_mul_f32_e32 v0, v4, v3
	v_add_u32_e32 v1, 0x1fd7c, v156
	ds_write_b32 v1, v0

.Ltp3_L1_l_b5:
	s_mov_b64 exec, s[6:7]
	s_waitcnt vmcnt(39)
	v_mfma_f32_32x32x16_bf16 v[0:15], v[16:19], v[72:75], 0
	s_waitcnt vmcnt(38)
	v_mfma_f32_32x32x16_bf16 v[0:15], v[20:23], v[60:63], v[0:15]
	s_waitcnt vmcnt(37)
	v_mfma_f32_32x32x16_bf16 v[0:15], v[24:27], v[64:67], v[0:15]
	s_waitcnt vmcnt(36)
	v_mfma_f32_32x32x16_bf16 v[0:15], v[28:31], v[52:55], v[0:15]
	s_and_saveexec_b64 s[6:7], s[0:1]
	s_cbranch_execz .Ltp3_L1_l_a6
	s_nop 9
	v_add_u32_e32 v4, 0xc0, v155
	v_cvt_f32_i32_e32 v4, v4
	v_mul_f32_e32 v4, 0xb9000400, v4
	v_mul_f32_e64 v5, |v144|, v4
	v_mul_f32_e64 v4, |v147|, v4
	v_mul_f32_e32 v5, 0x3fb8aa3b, v5
	v_mul_f32_e32 v4, 0x3fb8aa3b, v4
	v_exp_f32_e32 v5, v5
	v_exp_f32_e32 v4, v4
	v_mul_f32_e32 v0, v5, v0
	v_mul_f32_e32 v1, v4, v1
	v_mul_f32_e32 v2, v5, v2
	ds_write_b32 v157, v0 offset:768
	ds_write_b32 v156, v1 offset:64764
	v_add_u32_e32 v0, 0x10300, v157
	ds_write_b32 v0, v2
	v_mul_f32_e32 v0, v4, v3
	v_add_u32_e32 v1, 0x1fcfc, v156
	ds_write_b32 v1, v0

.Ltp3_L1_l_b6:
	s_mov_b64 exec, s[6:7]
	s_waitcnt vmcnt(35)
	v_mfma_f32_32x32x16_bf16 v[0:15], v[16:19], v[36:39], 0
	s_waitcnt vmcnt(34)
	v_mfma_f32_32x32x16_bf16 v[0:15], v[20:23], v[32:35], v[0:15]
	s_waitcnt vmcnt(33)
	v_mfma_f32_32x32x16_bf16 v[0:15], v[24:27], v[40:43], v[0:15]
	s_waitcnt vmcnt(32)
	v_mfma_f32_32x32x16_bf16 v[0:15], v[28:31], v[44:47], v[0:15]
	s_and_saveexec_b64 s[6:7], s[0:1]
	s_cbranch_execz .Ltp3_L1_l_a7
	s_nop 9
	v_add_u32_e32 v4, 0xe0, v155
	v_cvt_f32_i32_e32 v4, v4
	s_movk_i32 s8, 0x1f1f
	v_cmp_ne_u32_e32 vcc, s8, v155
	v_mul_f32_e32 v4, 0xb9000400, v4
	v_mul_f32_e64 v5, |v144|, v4
	v_mul_f32_e64 v4, |v147|, v4
	v_mul_f32_e32 v5, 0x3fb8aa3b, v5
	v_mul_f32_e32 v4, 0x3fb8aa3b, v4
	v_exp_f32_e32 v4, v4
	v_exp_f32_e32 v5, v5
	v_cndmask_b32_e32 v4, 0, v4, vcc
	v_mul_f32_e32 v0, v5, v0
	ds_write_b32 v157, v0 offset:896
	v_mul_f32_e32 v0, v4, v1
	ds_write_b32 v156, v0 offset:64636
	v_mul_f32_e32 v0, v5, v2
	v_add_u32_e32 v1, 0x10380, v157
	ds_write_b32 v1, v0
	v_mul_f32_e32 v0, v4, v3
	v_add_u32_e32 v1, 0x1fc7c, v156
	ds_write_b32 v1, v0

.Ltp3_L1_l_b7:
	s_mov_b64 exec, s[6:7]
	v_add_u32_e32 v153, 0x400, v153
	v_add_u32_e32 v154, 0xfffffc00, v154
	v_add_u32_e32 v155, 0x100, v155
	s_branch .LBB0_908
